# v97 (epilogue/prologue wait merges) + GEMM B0 fragment reads one phase earlier
# speedup vs baseline: 1.0112x; 1.0112x over previous
.LBB0_374:
	s_add_u32 s16, s14, 0x100
	s_addc_u32 s17, s15, 0
	s_add_i32 s49, 0, 0x10000
	s_cmp_eq_u32 s48, 40
	s_cselect_b32 s21, s7, s17
	s_cselect_b32 s20, s6, s16
	s_cselect_b32 s19, s9, s47
	s_cselect_b32 s18, s8, s46
	v_lshl_add_u64 v[162:163], s[14:15], 0, v[138:139]
	s_add_i32 m0, s35, 0xc000
	ds_read_b128 v[158:161], v166
	ds_read_b128 v[168:171], v166 offset:1024
	ds_read_b128 v[172:175], v166 offset:2048
	ds_read_b128 v[190:193], v166 offset:3072
	ds_read_b128 v[194:197], v166 offset:4096
	ds_read_b128 v[198:201], v166 offset:5120
	ds_read_b128 v[202:205], v166 offset:6144
	ds_read_b128 v[206:209], v166 offset:7168
	global_load_lds_dwordx4 v[162:163], off
	v_lshl_add_u64 v[162:163], s[14:15], 0, v[140:141]
	s_add_i32 m0, s35, 0xe000
	s_nop 0
	global_load_lds_dwordx4 v[162:163], off
	s_waitcnt lgkmcnt(8)
	s_barrier
	s_waitcnt lgkmcnt(0)
	s_waitcnt lgkmcnt(0)
	v_mfma_f32_16x16x32_bf16 v[126:129], v[142:145], v[158:161], v[126:129]
	v_mfma_f32_16x16x32_bf16 v[122:125], v[150:153], v[158:161], v[122:125]
	v_mfma_f32_16x16x32_bf16 v[110:113], v[142:145], v[172:175], v[110:113]
	v_mfma_f32_16x16x32_bf16 v[106:109], v[150:153], v[172:175], v[106:109]
	v_mfma_f32_16x16x32_bf16 v[94:97], v[142:145], v[194:197], v[94:97]
	v_mfma_f32_16x16x32_bf16 v[90:93], v[150:153], v[194:197], v[90:93]
	v_mfma_f32_16x16x32_bf16 v[78:81], v[142:145], v[202:205], v[78:81]
	v_mfma_f32_16x16x32_bf16 v[74:77], v[150:153], v[202:205], v[74:77]
	v_mfma_f32_16x16x32_bf16 v[126:129], v[146:149], v[168:171], v[126:129]
	v_mfma_f32_16x16x32_bf16 v[122:125], v[154:157], v[168:171], v[122:125]
	v_mfma_f32_16x16x32_bf16 v[110:113], v[146:149], v[190:193], v[110:113]
	v_mfma_f32_16x16x32_bf16 v[106:109], v[154:157], v[190:193], v[106:109]
	v_mfma_f32_16x16x32_bf16 v[94:97], v[146:149], v[198:201], v[94:97]
	v_mfma_f32_16x16x32_bf16 v[90:93], v[154:157], v[198:201], v[90:93]
	v_mfma_f32_16x16x32_bf16 v[78:81], v[146:149], v[206:209], v[78:81]
	v_mfma_f32_16x16x32_bf16 v[74:77], v[154:157], v[206:209], v[74:77]
	s_barrier
	s_add_i32 s50, 0, 0x14000
	v_add_u32_e32 v162, s50, v164
	s_add_i32 s14, s49, s34
	ds_read_b128 v[210:213], v162
	ds_read_b128 v[214:217], v162 offset:1024
	ds_read_b128 v[218:221], v162 offset:2048
	ds_read_b128 v[222:225], v162 offset:3072
	s_add_u32 s64, s18, 0x80
	s_addc_u32 s65, s19, 0
	s_mov_b32 m0, s14
	s_nop 0
	global_load_lds_dwordx4 v132, s[18:19]
	s_add_i32 m0, s14, 0x2000
	s_nop 0
	global_load_lds_dwordx4 v136, s[18:19]
	s_barrier
	s_waitcnt lgkmcnt(0)
	s_waitcnt lgkmcnt(0)
	v_mfma_f32_16x16x32_bf16 v[118:121], v[210:213], v[158:161], v[118:121]
	v_mfma_f32_16x16x32_bf16 v[114:117], v[218:221], v[158:161], v[114:117]
	v_mfma_f32_16x16x32_bf16 v[102:105], v[210:213], v[172:175], v[102:105]
	v_mfma_f32_16x16x32_bf16 v[98:101], v[218:221], v[172:175], v[98:101]
	v_mfma_f32_16x16x32_bf16 v[86:89], v[210:213], v[194:197], v[86:89]
	v_mfma_f32_16x16x32_bf16 v[82:85], v[218:221], v[194:197], v[82:85]
	v_mfma_f32_16x16x32_bf16 v[70:73], v[210:213], v[202:205], v[70:73]
	v_mfma_f32_16x16x32_bf16 v[66:69], v[218:221], v[202:205], v[66:69]
	v_mfma_f32_16x16x32_bf16 v[118:121], v[214:217], v[168:171], v[118:121]
	v_mfma_f32_16x16x32_bf16 v[114:117], v[222:225], v[168:171], v[114:117]
	v_mfma_f32_16x16x32_bf16 v[102:105], v[214:217], v[190:193], v[102:105]
	v_mfma_f32_16x16x32_bf16 v[98:101], v[222:225], v[190:193], v[98:101]
	v_mfma_f32_16x16x32_bf16 v[86:89], v[214:217], v[198:201], v[86:89]
	v_mfma_f32_16x16x32_bf16 v[82:85], v[222:225], v[198:201], v[82:85]
	v_mfma_f32_16x16x32_bf16 v[70:73], v[214:217], v[206:209], v[70:73]
	v_mfma_f32_16x16x32_bf16 v[66:69], v[222:225], v[206:209], v[66:69]
	s_barrier
	s_mov_b32 m0, s35
	s_add_u32 s62, s20, 0x80
	s_addc_u32 s63, s21, 0
	ds_read_b128 v[158:161], v166 offset:16384
	ds_read_b128 v[168:171], v166 offset:17408
	ds_read_b128 v[172:175], v166 offset:18432
	ds_read_b128 v[190:193], v166 offset:19456
	ds_read_b128 v[194:197], v166 offset:20480
	ds_read_b128 v[198:201], v166 offset:21504
	ds_read_b128 v[202:205], v166 offset:22528
	ds_read_b128 v[206:209], v166 offset:23552
	global_load_lds_dwordx4 v130, s[20:21]
	s_mov_b32 m0, s36
	s_nop 0
	global_load_lds_dwordx4 v134, s[20:21]
	s_waitcnt vmcnt(10)
	s_barrier
	s_waitcnt lgkmcnt(0)
	s_waitcnt lgkmcnt(0)
	v_mfma_f32_16x16x32_bf16 v[62:65], v[142:145], v[158:161], v[62:65]
	v_mfma_f32_16x16x32_bf16 v[58:61], v[150:153], v[158:161], v[58:61]
	v_mfma_f32_16x16x32_bf16 v[46:49], v[142:145], v[172:175], v[46:49]
	v_mfma_f32_16x16x32_bf16 v[42:45], v[150:153], v[172:175], v[42:45]
	v_mfma_f32_16x16x32_bf16 v[30:33], v[142:145], v[194:197], v[30:33]
	v_mfma_f32_16x16x32_bf16 v[26:29], v[150:153], v[194:197], v[26:29]
	v_mfma_f32_16x16x32_bf16 v[14:17], v[142:145], v[202:205], v[14:17]
	v_mfma_f32_16x16x32_bf16 v[10:13], v[150:153], v[202:205], v[10:13]
	v_mfma_f32_16x16x32_bf16 v[62:65], v[146:149], v[168:171], v[62:65]
	v_mfma_f32_16x16x32_bf16 v[58:61], v[154:157], v[168:171], v[58:61]
	v_mfma_f32_16x16x32_bf16 v[46:49], v[146:149], v[190:193], v[46:49]
	v_mfma_f32_16x16x32_bf16 v[42:45], v[154:157], v[190:193], v[42:45]
	v_mfma_f32_16x16x32_bf16 v[30:33], v[146:149], v[198:201], v[30:33]
	v_mfma_f32_16x16x32_bf16 v[26:29], v[154:157], v[198:201], v[26:29]
	v_mfma_f32_16x16x32_bf16 v[14:17], v[146:149], v[206:209], v[14:17]
	v_mfma_f32_16x16x32_bf16 v[10:13], v[154:157], v[206:209], v[10:13]
	s_barrier
	v_add_u32_e32 v154, 0x18000, v164
	ds_read_b128 v[142:145], v154
	ds_read_b128 v[146:149], v154 offset:1024
	ds_read_b128 v[150:153], v154 offset:2048
	ds_read_b128 v[154:157], v154 offset:3072
	s_add_u32 s14, s18, 0xb0000
	s_addc_u32 s15, s19, 0
	s_add_i32 s49, s50, s34
	s_mov_b32 m0, s49
	s_nop 0
	global_load_lds_dwordx4 v132, s[14:15]
	s_add_i32 m0, s49, 0x2000
	s_nop 0
	global_load_lds_dwordx4 v136, s[14:15]
	s_waitcnt vmcnt(6)
	s_barrier
	v_mfma_f32_16x16x32_bf16 v[54:57], v[210:213], v[158:161], v[54:57]
	v_mfma_f32_16x16x32_bf16 v[50:53], v[218:221], v[158:161], v[50:53]
	v_mfma_f32_16x16x32_bf16 v[38:41], v[210:213], v[172:175], v[38:41]
	v_mfma_f32_16x16x32_bf16 v[34:37], v[218:221], v[172:175], v[34:37]
	v_mfma_f32_16x16x32_bf16 v[22:25], v[210:213], v[194:197], v[22:25]
	v_mfma_f32_16x16x32_bf16 v[18:21], v[218:221], v[194:197], v[18:21]
	v_mfma_f32_16x16x32_bf16 v[6:9], v[210:213], v[202:205], v[6:9]
	v_mfma_f32_16x16x32_bf16 v[2:5], v[218:221], v[202:205], v[2:5]
	v_mfma_f32_16x16x32_bf16 v[54:57], v[214:217], v[168:171], v[54:57]
	v_mfma_f32_16x16x32_bf16 v[50:53], v[222:225], v[168:171], v[50:53]
	v_mfma_f32_16x16x32_bf16 v[38:41], v[214:217], v[190:193], v[38:41]
	v_mfma_f32_16x16x32_bf16 v[34:37], v[222:225], v[190:193], v[34:37]
	v_mfma_f32_16x16x32_bf16 v[22:25], v[214:217], v[198:201], v[22:25]
	v_mfma_f32_16x16x32_bf16 v[18:21], v[222:225], v[198:201], v[18:21]
	v_mfma_f32_16x16x32_bf16 v[6:9], v[214:217], v[206:209], v[6:9]
	v_mfma_f32_16x16x32_bf16 v[2:5], v[222:225], v[206:209], v[2:5]
	s_barrier
	s_add_i32 s49, 0, 0x18000
	s_add_u32 s14, s20, 0xb8000
	s_addc_u32 s15, s21, 0
	s_mov_b32 m0, s37
	ds_read_b128 v[158:161], v166 offset:32768
	ds_read_b128 v[168:171], v166 offset:33792
	ds_read_b128 v[172:175], v166 offset:34816
	ds_read_b128 v[190:193], v166 offset:35840
	ds_read_b128 v[194:197], v166 offset:36864
	ds_read_b128 v[198:201], v166 offset:37888
	ds_read_b128 v[202:205], v166 offset:38912
	ds_read_b128 v[206:209], v166 offset:39936
	global_load_lds_dwordx4 v130, s[14:15]
	s_mov_b32 m0, s38
	s_nop 0
	global_load_lds_dwordx4 v134, s[14:15]
	s_waitcnt lgkmcnt(8)
	s_barrier
	s_waitcnt lgkmcnt(0)
	s_waitcnt lgkmcnt(0)
	v_mfma_f32_16x16x32_bf16 v[126:129], v[142:145], v[158:161], v[126:129]
	v_mfma_f32_16x16x32_bf16 v[122:125], v[150:153], v[158:161], v[122:125]
	v_mfma_f32_16x16x32_bf16 v[110:113], v[142:145], v[172:175], v[110:113]
	v_mfma_f32_16x16x32_bf16 v[106:109], v[150:153], v[172:175], v[106:109]
	v_mfma_f32_16x16x32_bf16 v[94:97], v[142:145], v[194:197], v[94:97]
	v_mfma_f32_16x16x32_bf16 v[90:93], v[150:153], v[194:197], v[90:93]
	v_mfma_f32_16x16x32_bf16 v[78:81], v[142:145], v[202:205], v[78:81]
	v_mfma_f32_16x16x32_bf16 v[74:77], v[150:153], v[202:205], v[74:77]
	v_mfma_f32_16x16x32_bf16 v[126:129], v[146:149], v[168:171], v[126:129]
	v_mfma_f32_16x16x32_bf16 v[122:125], v[154:157], v[168:171], v[122:125]
	v_mfma_f32_16x16x32_bf16 v[110:113], v[146:149], v[190:193], v[110:113]
	v_mfma_f32_16x16x32_bf16 v[106:109], v[154:157], v[190:193], v[106:109]
	v_mfma_f32_16x16x32_bf16 v[94:97], v[146:149], v[198:201], v[94:97]
	v_mfma_f32_16x16x32_bf16 v[90:93], v[154:157], v[198:201], v[90:93]
	v_mfma_f32_16x16x32_bf16 v[78:81], v[146:149], v[206:209], v[78:81]
	v_mfma_f32_16x16x32_bf16 v[74:77], v[154:157], v[206:209], v[74:77]
	s_barrier
	s_add_i32 s20, 0, 0x1c000
	s_add_i32 s14, s49, s34
	v_add_u32_e32 v167, s20, v164
	s_mov_b32 m0, s14
	ds_read_b128 v[210:213], v167
	ds_read_b128 v[214:217], v167 offset:1024
	ds_read_b128 v[218:221], v167 offset:2048
	ds_read_b128 v[222:225], v167 offset:3072
	global_load_lds_dwordx4 v132, s[64:65]
	s_add_i32 m0, s14, 0x2000
	s_nop 0
	global_load_lds_dwordx4 v136, s[64:65]
	s_barrier
	s_waitcnt lgkmcnt(0)
	s_waitcnt lgkmcnt(0)
	v_mfma_f32_16x16x32_bf16 v[118:121], v[210:213], v[158:161], v[118:121]
	v_mfma_f32_16x16x32_bf16 v[114:117], v[218:221], v[158:161], v[114:117]
	v_mfma_f32_16x16x32_bf16 v[102:105], v[210:213], v[172:175], v[102:105]
	v_mfma_f32_16x16x32_bf16 v[98:101], v[218:221], v[172:175], v[98:101]
	v_mfma_f32_16x16x32_bf16 v[86:89], v[210:213], v[194:197], v[86:89]
	v_mfma_f32_16x16x32_bf16 v[82:85], v[218:221], v[194:197], v[82:85]
	v_mfma_f32_16x16x32_bf16 v[70:73], v[210:213], v[202:205], v[70:73]
	v_mfma_f32_16x16x32_bf16 v[66:69], v[218:221], v[202:205], v[66:69]
	v_mfma_f32_16x16x32_bf16 v[118:121], v[214:217], v[168:171], v[118:121]
	v_mfma_f32_16x16x32_bf16 v[114:117], v[222:225], v[168:171], v[114:117]
	v_mfma_f32_16x16x32_bf16 v[102:105], v[214:217], v[190:193], v[102:105]
	v_mfma_f32_16x16x32_bf16 v[98:101], v[222:225], v[190:193], v[98:101]
	v_mfma_f32_16x16x32_bf16 v[86:89], v[214:217], v[198:201], v[86:89]
	v_mfma_f32_16x16x32_bf16 v[82:85], v[222:225], v[198:201], v[82:85]
	v_mfma_f32_16x16x32_bf16 v[70:73], v[214:217], v[206:209], v[70:73]
	v_mfma_f32_16x16x32_bf16 v[66:69], v[222:225], v[206:209], v[66:69]
	s_barrier
	s_mov_b32 m0, s39
	ds_read_b128 v[158:161], v166 offset:49152
	ds_read_b128 v[168:171], v166 offset:50176
	ds_read_b128 v[172:175], v166 offset:51200
	ds_read_b128 v[190:193], v166 offset:52224
	ds_read_b128 v[194:197], v166 offset:53248
	ds_read_b128 v[198:201], v166 offset:54272
	ds_read_b128 v[202:205], v166 offset:55296
	ds_read_b128 v[206:209], v166 offset:56320
	global_load_lds_dwordx4 v130, s[62:63]
	s_mov_b32 m0, s40
	s_nop 0
	global_load_lds_dwordx4 v134, s[62:63]
	s_waitcnt vmcnt(10)
	s_barrier
	s_waitcnt lgkmcnt(0)
	s_waitcnt lgkmcnt(0)
	v_mfma_f32_16x16x32_bf16 v[62:65], v[142:145], v[158:161], v[62:65]
	v_mfma_f32_16x16x32_bf16 v[58:61], v[150:153], v[158:161], v[58:61]
	v_mfma_f32_16x16x32_bf16 v[46:49], v[142:145], v[172:175], v[46:49]
	v_mfma_f32_16x16x32_bf16 v[42:45], v[150:153], v[172:175], v[42:45]
	v_mfma_f32_16x16x32_bf16 v[30:33], v[142:145], v[194:197], v[30:33]
	v_mfma_f32_16x16x32_bf16 v[26:29], v[150:153], v[194:197], v[26:29]
	v_mfma_f32_16x16x32_bf16 v[14:17], v[142:145], v[202:205], v[14:17]
	v_mfma_f32_16x16x32_bf16 v[10:13], v[150:153], v[202:205], v[10:13]
	v_mfma_f32_16x16x32_bf16 v[62:65], v[146:149], v[168:171], v[62:65]
	v_mfma_f32_16x16x32_bf16 v[58:61], v[154:157], v[168:171], v[58:61]
	v_mfma_f32_16x16x32_bf16 v[46:49], v[146:149], v[190:193], v[46:49]
	v_mfma_f32_16x16x32_bf16 v[42:45], v[154:157], v[190:193], v[42:45]
	v_mfma_f32_16x16x32_bf16 v[30:33], v[146:149], v[198:201], v[30:33]
	v_mfma_f32_16x16x32_bf16 v[26:29], v[154:157], v[198:201], v[26:29]
	v_mfma_f32_16x16x32_bf16 v[14:17], v[146:149], v[206:209], v[14:17]
	v_mfma_f32_16x16x32_bf16 v[10:13], v[154:157], v[206:209], v[10:13]
	s_barrier
	v_add_u32_e32 v154, 0x10000, v164
	ds_read_b128 v[142:145], v154
	ds_read_b128 v[146:149], v154 offset:1024
	ds_read_b128 v[150:153], v154 offset:2048
	ds_read_b128 v[154:157], v154 offset:3072
	s_add_u32 s14, s18, 0xb0080
	s_addc_u32 s15, s19, 0
	s_add_i32 s18, s20, s34
	s_mov_b32 m0, s18
	s_nop 0
	global_load_lds_dwordx4 v132, s[14:15]
	s_add_i32 m0, s18, 0x2000
	s_nop 0
	global_load_lds_dwordx4 v136, s[14:15]
	s_waitcnt vmcnt(6)
	s_barrier
	v_mfma_f32_16x16x32_bf16 v[54:57], v[210:213], v[158:161], v[54:57]
	v_mfma_f32_16x16x32_bf16 v[50:53], v[218:221], v[158:161], v[50:53]
	v_mfma_f32_16x16x32_bf16 v[38:41], v[210:213], v[172:175], v[38:41]
	v_mfma_f32_16x16x32_bf16 v[34:37], v[218:221], v[172:175], v[34:37]
	v_mfma_f32_16x16x32_bf16 v[22:25], v[210:213], v[194:197], v[22:25]
	v_mfma_f32_16x16x32_bf16 v[18:21], v[218:221], v[194:197], v[18:21]
	v_mfma_f32_16x16x32_bf16 v[6:9], v[210:213], v[202:205], v[6:9]
	v_mfma_f32_16x16x32_bf16 v[2:5], v[218:221], v[202:205], v[2:5]
	v_mfma_f32_16x16x32_bf16 v[54:57], v[214:217], v[168:171], v[54:57]
	v_mfma_f32_16x16x32_bf16 v[50:53], v[222:225], v[168:171], v[50:53]
	v_mfma_f32_16x16x32_bf16 v[38:41], v[214:217], v[190:193], v[38:41]
	v_mfma_f32_16x16x32_bf16 v[34:37], v[222:225], v[190:193], v[34:37]
	v_mfma_f32_16x16x32_bf16 v[22:25], v[214:217], v[198:201], v[22:25]
	v_mfma_f32_16x16x32_bf16 v[18:21], v[222:225], v[198:201], v[18:21]
	v_mfma_f32_16x16x32_bf16 v[6:9], v[214:217], v[206:209], v[6:9]
	v_mfma_f32_16x16x32_bf16 v[2:5], v[222:225], v[206:209], v[2:5]
	s_barrier
	s_add_i32 s48, s48, 2
	s_add_u32 s46, s46, 0x100
	s_addc_u32 s47, s47, 0
	s_cmp_gt_u32 s48, 41
	s_mov_b64 s[14:15], s[16:17]
	s_cbranch_scc0 .LBB0_374
	s_waitcnt lgkmcnt(0)
	s_ashr_i32 s14, s33, 5
	s_mul_hi_i32 s15, s14, 0x9000
	s_mul_i32 s14, s14, 0x9000
	v_lshl_or_b32 v158, s45, 8, v165
	s_add_u32 s14, s26, s14
	s_addc_u32 s15, s27, s15
	v_ashrrev_i32_e32 v159, 31, v158
	v_lshl_add_u64 v[160:161], v[158:159], 2, s[14:15]
	global_load_dwordx4 v[142:145], v[160:161], off offset:16
	global_load_dwordx4 v[146:149], v[160:161], off
	v_lshl_add_u32 v162, s33, 8, v1
	v_ashrrev_i32_e32 v163, 31, v162
	v_lshlrev_b64 v[150:151], 12, v[162:163]
	v_lshl_add_u64 v[150:151], s[12:13], 0, v[150:151]
	v_lshl_add_u64 v[150:151], v[158:159], 1, v[150:151]
	v_mov_b32_e32 v152, 0x10000
	v_mov_b32_e32 v153, 0
	global_load_dwordx4 v[174:177], v[150:151], off offset:2048
	global_load_dwordx4 v[186:189], v[150:151], off offset:2304
	v_lshl_add_u64 v[150:151], v[150:151], 0, v[152:153]
	global_load_dwordx4 v[190:193], v[150:151], off offset:2048
	global_load_dwordx4 v[194:197], v[150:151], off offset:2304
	v_lshl_add_u64 v[150:151], v[150:151], 0, v[152:153]
	global_load_dwordx4 v[198:201], v[150:151], off offset:2048
	global_load_dwordx4 v[202:205], v[150:151], off offset:2304
	v_lshl_add_u64 v[150:151], v[150:151], 0, v[152:153]
	global_load_dwordx4 v[206:209], v[150:151], off offset:2048
	global_load_dwordx4 v[210:213], v[150:151], off offset:2304
	v_mov_b32_e32 v152, 0x50000
	v_lshl_add_u64 v[150:151], v[150:151], 0, v[152:153]
	v_mov_b32_e32 v152, 0x10000
	global_load_dwordx4 v[214:217], v[150:151], off offset:2048
	global_load_dwordx4 v[218:221], v[150:151], off offset:2304
	v_lshl_add_u64 v[150:151], v[150:151], 0, v[152:153]
	global_load_dwordx4 v[222:225], v[150:151], off offset:2048
	global_load_dwordx4 v[226:229], v[150:151], off offset:2304
	v_lshl_add_u64 v[150:151], v[150:151], 0, v[152:153]
	global_load_dwordx4 v[230:233], v[150:151], off offset:2048
	global_load_dwordx4 v[236:239], v[150:151], off offset:2304
	v_lshl_add_u64 v[150:151], v[150:151], 0, v[152:153]
	global_load_dwordx4 v[246:249], v[150:151], off offset:2048
	global_load_dwordx4 v[250:253], v[150:151], off offset:2304
	s_mov_b64 s[14:15], 0x80000
	s_and_b64 vcc, exec, s[4:5]
	s_mov_b32 s45, s43
	s_mov_b32 s33, s44
	s_mov_b64 s[16:17], s[8:9]
	s_waitcnt vmcnt(16)
	v_pk_add_f32 v[144:145], v[144:145], 1.0 op_sel_hi:[1,0]
	v_pk_add_f32 v[148:149], v[148:149], 1.0 op_sel_hi:[1,0]
	v_pk_add_f32 v[146:147], v[146:147], 1.0 op_sel_hi:[1,0]
	v_pk_add_f32 v[142:143], v[142:143], 1.0 op_sel_hi:[1,0]
	v_pk_mul_f32 v[152:153], v[148:149], 0.5 op_sel_hi:[1,0]
	v_pk_mul_f32 v[156:157], v[146:147], 0.5 op_sel_hi:[1,0]
	v_pk_mul_f32 v[150:151], v[144:145], 0.5 op_sel_hi:[1,0]
	v_pk_mul_f32 v[154:155], v[142:143], 0.5 op_sel_hi:[1,0]
	global_load_dwordx4 v[142:145], v[160:161], off offset:528
	global_load_dwordx4 v[146:149], v[160:161], off offset:512
	s_waitcnt vmcnt(0)
	v_pk_add_f32 v[144:145], v[144:145], 1.0 op_sel_hi:[1,0]
	v_pk_add_f32 v[148:149], v[148:149], 1.0 op_sel_hi:[1,0]
	v_pk_add_f32 v[160:161], v[146:147], 1.0 op_sel_hi:[1,0]
	v_pk_mul_f32 v[146:147], v[148:149], 0.5 op_sel_hi:[1,0]
	v_pk_mul_f32 v[148:149], v[160:161], 0.5 op_sel_hi:[1,0]
	v_pk_add_f32 v[160:161], v[142:143], 1.0 op_sel_hi:[1,0]
	v_pk_mul_f32 v[142:143], v[144:145], 0.5 op_sel_hi:[1,0]
	v_pk_mul_f32 v[144:145], v[160:161], 0.5 op_sel_hi:[1,0]
	v_lshlrev_b64 v[160:161], 12, v[162:163]
	v_lshl_add_u64 v[168:169], s[12:13], 0, v[160:161]
	v_lshlrev_b64 v[160:161], 1, v[158:159]
	v_lshl_add_u64 v[158:159], v[168:169], 0, v[160:161]
	v_mov_b32_e32 v168, v174
	v_mov_b32_e32 v169, v175
	v_mov_b32_e32 v170, v176
	v_mov_b32_e32 v171, v177
	s_nop 0
	v_lshlrev_b32_e32 v172, 16, v168
	v_and_b32_e32 v173, 0xffff0000, v168
	v_lshlrev_b32_e32 v168, 16, v169
	v_and_b32_e32 v169, 0xffff0000, v169
	v_pk_fma_f32 v[128:129], v[128:129], v[152:153], v[168:169]
	v_lshlrev_b32_e32 v168, 16, v170
	v_and_b32_e32 v169, 0xffff0000, v170
	v_pk_fma_f32 v[168:169], v[122:123], v[154:155], v[168:169]
	v_lshlrev_b32_e32 v122, 16, v171
	v_and_b32_e32 v123, 0xffff0000, v171
	v_pk_fma_f32 v[126:127], v[126:127], v[156:157], v[172:173]
	v_pk_fma_f32 v[170:171], v[124:125], v[150:151], v[122:123]
	v_cvt_pk_bf16_f32 v122, v126, v127
	v_cvt_pk_bf16_f32 v123, v128, v129
	v_cvt_pk_bf16_f32 v124, v168, v169
	v_cvt_pk_bf16_f32 v125, v170, v171
	global_store_dwordx4 v[158:159], v[122:125], off offset:2048
	s_nop 1
	v_mov_b32_e32 v122, v186
	v_mov_b32_e32 v123, v187
	v_mov_b32_e32 v124, v188
	v_mov_b32_e32 v125, v189
	s_nop 0
	v_lshlrev_b32_e32 v126, 16, v122
	v_and_b32_e32 v127, 0xffff0000, v122
	v_lshlrev_b32_e32 v122, 16, v123
	v_and_b32_e32 v123, 0xffff0000, v123
	v_pk_fma_f32 v[120:121], v[120:121], v[146:147], v[122:123]
	v_lshlrev_b32_e32 v122, 16, v124
	v_and_b32_e32 v123, 0xffff0000, v124
	v_pk_fma_f32 v[122:123], v[114:115], v[144:145], v[122:123]
	v_lshlrev_b32_e32 v114, 16, v125
	v_and_b32_e32 v115, 0xffff0000, v125
	v_pk_fma_f32 v[118:119], v[118:119], v[148:149], v[126:127]
	v_pk_fma_f32 v[124:125], v[116:117], v[142:143], v[114:115]
	v_cvt_pk_bf16_f32 v114, v118, v119
	v_cvt_pk_bf16_f32 v115, v120, v121
	v_cvt_pk_bf16_f32 v116, v122, v123
	v_cvt_pk_bf16_f32 v117, v124, v125
	global_store_dwordx4 v[158:159], v[114:117], off offset:2304
	s_nop 1
	v_or_b32_e32 v114, 16, v162
	v_ashrrev_i32_e32 v115, 31, v114
	v_lshlrev_b64 v[114:115], 12, v[114:115]
	v_lshl_add_u64 v[114:115], s[12:13], 0, v[114:115]
	v_lshl_add_u64 v[118:119], v[114:115], 0, v[160:161]
	v_mov_b32_e32 v114, v190
	v_mov_b32_e32 v115, v191
	v_mov_b32_e32 v116, v192
	v_mov_b32_e32 v117, v193
	s_nop 0
	v_lshlrev_b32_e32 v120, 16, v114
	v_and_b32_e32 v121, 0xffff0000, v114
	v_lshlrev_b32_e32 v114, 16, v115
	v_and_b32_e32 v115, 0xffff0000, v115
	v_pk_fma_f32 v[112:113], v[112:113], v[152:153], v[114:115]
	v_lshlrev_b32_e32 v114, 16, v116
	v_and_b32_e32 v115, 0xffff0000, v116
	v_pk_fma_f32 v[114:115], v[106:107], v[154:155], v[114:115]
	v_lshlrev_b32_e32 v106, 16, v117
	v_and_b32_e32 v107, 0xffff0000, v117
	v_pk_fma_f32 v[110:111], v[110:111], v[156:157], v[120:121]
	v_pk_fma_f32 v[116:117], v[108:109], v[150:151], v[106:107]
	v_cvt_pk_bf16_f32 v106, v110, v111
	v_cvt_pk_bf16_f32 v107, v112, v113
	v_cvt_pk_bf16_f32 v108, v114, v115
	v_cvt_pk_bf16_f32 v109, v116, v117
	global_store_dwordx4 v[118:119], v[106:109], off offset:2048
	s_nop 1
	v_mov_b32_e32 v106, v194
	v_mov_b32_e32 v107, v195
	v_mov_b32_e32 v108, v196
	v_mov_b32_e32 v109, v197
	s_nop 0
	v_lshlrev_b32_e32 v110, 16, v106
	v_and_b32_e32 v111, 0xffff0000, v106
	v_lshlrev_b32_e32 v106, 16, v107
	v_and_b32_e32 v107, 0xffff0000, v107
	v_pk_fma_f32 v[104:105], v[104:105], v[146:147], v[106:107]
	v_lshlrev_b32_e32 v106, 16, v108
	v_and_b32_e32 v107, 0xffff0000, v108
	v_pk_fma_f32 v[106:107], v[98:99], v[144:145], v[106:107]
	v_lshlrev_b32_e32 v98, 16, v109
	v_and_b32_e32 v99, 0xffff0000, v109
	v_pk_fma_f32 v[102:103], v[102:103], v[148:149], v[110:111]
	v_pk_fma_f32 v[108:109], v[100:101], v[142:143], v[98:99]
	v_cvt_pk_bf16_f32 v98, v102, v103
	v_cvt_pk_bf16_f32 v99, v104, v105
	v_cvt_pk_bf16_f32 v100, v106, v107
	v_cvt_pk_bf16_f32 v101, v108, v109
	global_store_dwordx4 v[118:119], v[98:101], off offset:2304
	s_nop 1
	v_or_b32_e32 v98, 32, v162
	v_ashrrev_i32_e32 v99, 31, v98
	v_lshlrev_b64 v[98:99], 12, v[98:99]
	v_lshl_add_u64 v[98:99], s[12:13], 0, v[98:99]
	v_lshl_add_u64 v[102:103], v[98:99], 0, v[160:161]
	v_mov_b32_e32 v98, v198
	v_mov_b32_e32 v99, v199
	v_mov_b32_e32 v100, v200
	v_mov_b32_e32 v101, v201
	s_nop 0
	v_lshlrev_b32_e32 v104, 16, v98
	v_and_b32_e32 v105, 0xffff0000, v98
	v_lshlrev_b32_e32 v98, 16, v99
	v_and_b32_e32 v99, 0xffff0000, v99
	v_pk_fma_f32 v[96:97], v[96:97], v[152:153], v[98:99]
	v_lshlrev_b32_e32 v98, 16, v100
	v_and_b32_e32 v99, 0xffff0000, v100
	v_pk_fma_f32 v[98:99], v[90:91], v[154:155], v[98:99]
	v_lshlrev_b32_e32 v90, 16, v101
	v_and_b32_e32 v91, 0xffff0000, v101
	v_pk_fma_f32 v[94:95], v[94:95], v[156:157], v[104:105]
	v_pk_fma_f32 v[100:101], v[92:93], v[150:151], v[90:91]
	v_cvt_pk_bf16_f32 v90, v94, v95
	v_cvt_pk_bf16_f32 v91, v96, v97
	v_cvt_pk_bf16_f32 v92, v98, v99
	v_cvt_pk_bf16_f32 v93, v100, v101
	global_store_dwordx4 v[102:103], v[90:93], off offset:2048
	s_nop 1
	v_mov_b32_e32 v90, v202
	v_mov_b32_e32 v91, v203
	v_mov_b32_e32 v92, v204
	v_mov_b32_e32 v93, v205
	s_nop 0
	v_lshlrev_b32_e32 v94, 16, v90
	v_and_b32_e32 v95, 0xffff0000, v90
	v_lshlrev_b32_e32 v90, 16, v91
	v_and_b32_e32 v91, 0xffff0000, v91
	v_pk_fma_f32 v[88:89], v[88:89], v[146:147], v[90:91]
	v_lshlrev_b32_e32 v90, 16, v92
	v_and_b32_e32 v91, 0xffff0000, v92
	v_pk_fma_f32 v[90:91], v[82:83], v[144:145], v[90:91]
	v_lshlrev_b32_e32 v82, 16, v93
	v_and_b32_e32 v83, 0xffff0000, v93
	v_pk_fma_f32 v[86:87], v[86:87], v[148:149], v[94:95]
	v_pk_fma_f32 v[92:93], v[84:85], v[142:143], v[82:83]
	v_cvt_pk_bf16_f32 v82, v86, v87
	v_cvt_pk_bf16_f32 v83, v88, v89
	v_cvt_pk_bf16_f32 v84, v90, v91
	v_cvt_pk_bf16_f32 v85, v92, v93
	global_store_dwordx4 v[102:103], v[82:85], off offset:2304
	s_nop 1
	v_or_b32_e32 v82, 48, v162
	v_ashrrev_i32_e32 v83, 31, v82
	v_lshlrev_b64 v[82:83], 12, v[82:83]
	v_lshl_add_u64 v[82:83], s[12:13], 0, v[82:83]
	v_lshl_add_u64 v[82:83], v[82:83], 0, v[160:161]
	v_mov_b32_e32 v84, v206
	v_mov_b32_e32 v85, v207
	v_mov_b32_e32 v86, v208
	v_mov_b32_e32 v87, v209
	s_nop 0
	v_lshlrev_b32_e32 v88, 16, v84
	v_and_b32_e32 v89, 0xffff0000, v84
	v_lshlrev_b32_e32 v84, 16, v85
	v_and_b32_e32 v85, 0xffff0000, v85
	v_pk_fma_f32 v[80:81], v[80:81], v[152:153], v[84:85]
	v_lshlrev_b32_e32 v84, 16, v86
	v_and_b32_e32 v85, 0xffff0000, v86
	v_pk_fma_f32 v[84:85], v[74:75], v[154:155], v[84:85]
	v_lshlrev_b32_e32 v74, 16, v87
	v_and_b32_e32 v75, 0xffff0000, v87
	v_pk_fma_f32 v[78:79], v[78:79], v[156:157], v[88:89]
	v_pk_fma_f32 v[86:87], v[76:77], v[150:151], v[74:75]
	v_cvt_pk_bf16_f32 v74, v78, v79
	v_cvt_pk_bf16_f32 v75, v80, v81
	v_cvt_pk_bf16_f32 v76, v84, v85
	v_cvt_pk_bf16_f32 v77, v86, v87
	global_store_dwordx4 v[82:83], v[74:77], off offset:2048
	s_nop 1
	v_mov_b32_e32 v74, v210
	v_mov_b32_e32 v75, v211
	v_mov_b32_e32 v76, v212
	v_mov_b32_e32 v77, v213
	s_nop 0
	v_lshlrev_b32_e32 v78, 16, v74
	v_and_b32_e32 v79, 0xffff0000, v74
	v_lshlrev_b32_e32 v74, 16, v75
	v_and_b32_e32 v75, 0xffff0000, v75
	v_pk_fma_f32 v[72:73], v[72:73], v[146:147], v[74:75]
	v_lshlrev_b32_e32 v74, 16, v76
	v_and_b32_e32 v75, 0xffff0000, v76
	v_pk_fma_f32 v[74:75], v[66:67], v[144:145], v[74:75]
	v_lshlrev_b32_e32 v66, 16, v77
	v_and_b32_e32 v67, 0xffff0000, v77
	v_pk_fma_f32 v[70:71], v[70:71], v[148:149], v[78:79]
	v_pk_fma_f32 v[76:77], v[68:69], v[142:143], v[66:67]
	v_cvt_pk_bf16_f32 v66, v70, v71
	v_cvt_pk_bf16_f32 v67, v72, v73
	v_cvt_pk_bf16_f32 v68, v74, v75
	v_cvt_pk_bf16_f32 v69, v76, v77
	v_lshl_add_u64 v[70:71], v[158:159], 0, s[14:15]
	global_store_dwordx4 v[82:83], v[66:69], off offset:2304
	s_nop 1
	v_mov_b32_e32 v66, v214
	v_mov_b32_e32 v67, v215
	v_mov_b32_e32 v68, v216
	v_mov_b32_e32 v69, v217
	s_mov_b64 s[14:15], 0x90000
	s_nop 0
	v_lshlrev_b32_e32 v72, 16, v66
	v_and_b32_e32 v73, 0xffff0000, v66
	v_lshlrev_b32_e32 v66, 16, v67
	v_and_b32_e32 v67, 0xffff0000, v67
	v_pk_fma_f32 v[64:65], v[64:65], v[152:153], v[66:67]
	v_lshlrev_b32_e32 v66, 16, v68
	v_and_b32_e32 v67, 0xffff0000, v68
	v_pk_fma_f32 v[66:67], v[58:59], v[154:155], v[66:67]
	v_lshlrev_b32_e32 v58, 16, v69
	v_and_b32_e32 v59, 0xffff0000, v69
	v_pk_fma_f32 v[62:63], v[62:63], v[156:157], v[72:73]
	v_pk_fma_f32 v[68:69], v[60:61], v[150:151], v[58:59]
	v_cvt_pk_bf16_f32 v58, v62, v63
	v_cvt_pk_bf16_f32 v59, v64, v65
	v_cvt_pk_bf16_f32 v60, v66, v67
	v_cvt_pk_bf16_f32 v61, v68, v69
	global_store_dwordx4 v[70:71], v[58:61], off offset:2048
	s_nop 1
	v_mov_b32_e32 v58, v218
	v_mov_b32_e32 v59, v219
	v_mov_b32_e32 v60, v220
	v_mov_b32_e32 v61, v221
	s_nop 0
	v_lshlrev_b32_e32 v62, 16, v58
	v_and_b32_e32 v63, 0xffff0000, v58
	v_lshlrev_b32_e32 v58, 16, v59
	v_and_b32_e32 v59, 0xffff0000, v59
	v_pk_fma_f32 v[56:57], v[56:57], v[146:147], v[58:59]
	v_lshlrev_b32_e32 v58, 16, v60
	v_and_b32_e32 v59, 0xffff0000, v60
	v_pk_fma_f32 v[58:59], v[50:51], v[144:145], v[58:59]
	v_lshlrev_b32_e32 v50, 16, v61
	v_and_b32_e32 v51, 0xffff0000, v61
	v_pk_fma_f32 v[54:55], v[54:55], v[148:149], v[62:63]
	v_pk_fma_f32 v[60:61], v[52:53], v[142:143], v[50:51]
	v_cvt_pk_bf16_f32 v50, v54, v55
	v_cvt_pk_bf16_f32 v51, v56, v57
	v_cvt_pk_bf16_f32 v52, v58, v59
	v_cvt_pk_bf16_f32 v53, v60, v61
	v_lshl_add_u64 v[54:55], v[158:159], 0, s[14:15]
	global_store_dwordx4 v[70:71], v[50:53], off offset:2304
	s_nop 1
	v_mov_b32_e32 v50, v222
	v_mov_b32_e32 v51, v223
	v_mov_b32_e32 v52, v224
	v_mov_b32_e32 v53, v225
	s_mov_b64 s[14:15], 0xa0000
	s_nop 0
	v_lshlrev_b32_e32 v56, 16, v50
	v_and_b32_e32 v57, 0xffff0000, v50
	v_lshlrev_b32_e32 v50, 16, v51
	v_and_b32_e32 v51, 0xffff0000, v51
	v_pk_fma_f32 v[48:49], v[48:49], v[152:153], v[50:51]
	v_lshlrev_b32_e32 v50, 16, v52
	v_and_b32_e32 v51, 0xffff0000, v52
	v_pk_fma_f32 v[50:51], v[42:43], v[154:155], v[50:51]
	v_lshlrev_b32_e32 v42, 16, v53
	v_and_b32_e32 v43, 0xffff0000, v53
	v_pk_fma_f32 v[46:47], v[46:47], v[156:157], v[56:57]
	v_pk_fma_f32 v[52:53], v[44:45], v[150:151], v[42:43]
	v_cvt_pk_bf16_f32 v42, v46, v47
	v_cvt_pk_bf16_f32 v43, v48, v49
	v_cvt_pk_bf16_f32 v44, v50, v51
	v_cvt_pk_bf16_f32 v45, v52, v53
	global_store_dwordx4 v[54:55], v[42:45], off offset:2048
	s_nop 1
	v_mov_b32_e32 v42, v226
	v_mov_b32_e32 v43, v227
	v_mov_b32_e32 v44, v228
	v_mov_b32_e32 v45, v229
	s_nop 0
	v_lshlrev_b32_e32 v46, 16, v42
	v_and_b32_e32 v47, 0xffff0000, v42
	v_lshlrev_b32_e32 v42, 16, v43
	v_and_b32_e32 v43, 0xffff0000, v43
	v_pk_fma_f32 v[40:41], v[40:41], v[146:147], v[42:43]
	v_lshlrev_b32_e32 v42, 16, v44
	v_and_b32_e32 v43, 0xffff0000, v44
	v_pk_fma_f32 v[42:43], v[34:35], v[144:145], v[42:43]
	v_lshlrev_b32_e32 v34, 16, v45
	v_and_b32_e32 v35, 0xffff0000, v45
	v_pk_fma_f32 v[38:39], v[38:39], v[148:149], v[46:47]
	v_pk_fma_f32 v[44:45], v[36:37], v[142:143], v[34:35]
	v_cvt_pk_bf16_f32 v34, v38, v39
	v_cvt_pk_bf16_f32 v35, v40, v41
	v_cvt_pk_bf16_f32 v36, v42, v43
	v_cvt_pk_bf16_f32 v37, v44, v45
	v_lshl_add_u64 v[38:39], v[158:159], 0, s[14:15]
	global_store_dwordx4 v[54:55], v[34:37], off offset:2304
	s_nop 1
	v_mov_b32_e32 v34, v230
	v_mov_b32_e32 v35, v231
	v_mov_b32_e32 v36, v232
	v_mov_b32_e32 v37, v233
	s_mov_b64 s[14:15], 0xb0000
	s_nop 0
	v_lshlrev_b32_e32 v40, 16, v34
	v_and_b32_e32 v41, 0xffff0000, v34
	v_lshlrev_b32_e32 v34, 16, v35
	v_and_b32_e32 v35, 0xffff0000, v35
	v_pk_fma_f32 v[32:33], v[32:33], v[152:153], v[34:35]
	v_lshlrev_b32_e32 v34, 16, v36
	v_and_b32_e32 v35, 0xffff0000, v36
	v_pk_fma_f32 v[34:35], v[26:27], v[154:155], v[34:35]
	v_lshlrev_b32_e32 v26, 16, v37
	v_and_b32_e32 v27, 0xffff0000, v37
	v_pk_fma_f32 v[30:31], v[30:31], v[156:157], v[40:41]
	v_pk_fma_f32 v[36:37], v[28:29], v[150:151], v[26:27]
	v_cvt_pk_bf16_f32 v26, v30, v31
	v_cvt_pk_bf16_f32 v27, v32, v33
	v_cvt_pk_bf16_f32 v28, v34, v35
	v_cvt_pk_bf16_f32 v29, v36, v37
	global_store_dwordx4 v[38:39], v[26:29], off offset:2048
	s_nop 1
	v_mov_b32_e32 v26, v236
	v_mov_b32_e32 v27, v237
	v_mov_b32_e32 v28, v238
	v_mov_b32_e32 v29, v239
	s_nop 0
	v_lshlrev_b32_e32 v30, 16, v26
	v_and_b32_e32 v31, 0xffff0000, v26
	v_lshlrev_b32_e32 v26, 16, v27
	v_and_b32_e32 v27, 0xffff0000, v27
	v_pk_fma_f32 v[24:25], v[24:25], v[146:147], v[26:27]
	v_lshlrev_b32_e32 v26, 16, v28
	v_and_b32_e32 v27, 0xffff0000, v28
	v_pk_fma_f32 v[26:27], v[18:19], v[144:145], v[26:27]
	v_lshlrev_b32_e32 v18, 16, v29
	v_and_b32_e32 v19, 0xffff0000, v29
	v_pk_fma_f32 v[22:23], v[22:23], v[148:149], v[30:31]
	v_pk_fma_f32 v[28:29], v[20:21], v[142:143], v[18:19]
	v_cvt_pk_bf16_f32 v18, v22, v23
	v_cvt_pk_bf16_f32 v19, v24, v25
	v_cvt_pk_bf16_f32 v20, v26, v27
	v_cvt_pk_bf16_f32 v21, v28, v29
	global_store_dwordx4 v[38:39], v[18:21], off offset:2304
	s_nop 1
	v_lshl_add_u64 v[18:19], v[158:159], 0, s[14:15]
	v_mov_b32_e32 v20, v246
	v_mov_b32_e32 v21, v247
	v_mov_b32_e32 v22, v248
	v_mov_b32_e32 v23, v249
	s_mov_b64 s[14:15], s[6:7]
	s_nop 0
	v_lshlrev_b32_e32 v24, 16, v20
	v_and_b32_e32 v25, 0xffff0000, v20
	v_lshlrev_b32_e32 v20, 16, v21
	v_and_b32_e32 v21, 0xffff0000, v21
	v_pk_fma_f32 v[16:17], v[16:17], v[152:153], v[20:21]
	v_lshlrev_b32_e32 v20, 16, v22
	v_and_b32_e32 v21, 0xffff0000, v22
	v_pk_fma_f32 v[20:21], v[10:11], v[154:155], v[20:21]
	v_lshlrev_b32_e32 v10, 16, v23
	v_and_b32_e32 v11, 0xffff0000, v23
	v_pk_fma_f32 v[14:15], v[14:15], v[156:157], v[24:25]
	v_pk_fma_f32 v[22:23], v[12:13], v[150:151], v[10:11]
	v_cvt_pk_bf16_f32 v10, v14, v15
	v_cvt_pk_bf16_f32 v11, v16, v17
	v_cvt_pk_bf16_f32 v12, v20, v21
	v_cvt_pk_bf16_f32 v13, v22, v23
	global_store_dwordx4 v[18:19], v[10:13], off offset:2048
	s_nop 1
	v_mov_b32_e32 v10, v250
	v_mov_b32_e32 v11, v251
	v_mov_b32_e32 v12, v252
	v_mov_b32_e32 v13, v253
	s_nop 0
	v_lshlrev_b32_e32 v14, 16, v10
	v_and_b32_e32 v15, 0xffff0000, v10
	v_lshlrev_b32_e32 v10, 16, v11
	v_and_b32_e32 v11, 0xffff0000, v11
	v_pk_fma_f32 v[8:9], v[8:9], v[146:147], v[10:11]
	v_lshlrev_b32_e32 v10, 16, v12
	v_and_b32_e32 v11, 0xffff0000, v12
	v_pk_fma_f32 v[10:11], v[2:3], v[144:145], v[10:11]
	v_lshlrev_b32_e32 v2, 16, v13
	v_and_b32_e32 v3, 0xffff0000, v13
	v_pk_fma_f32 v[6:7], v[6:7], v[148:149], v[14:15]
	v_pk_fma_f32 v[12:13], v[4:5], v[142:143], v[2:3]
	v_cvt_pk_bf16_f32 v2, v6, v7
	v_cvt_pk_bf16_f32 v3, v8, v9
	v_cvt_pk_bf16_f32 v4, v10, v11
	v_cvt_pk_bf16_f32 v5, v12, v13
	global_store_dwordx4 v[18:19], v[2:5], off offset:2304
	s_cbranch_vccz .LBB0_363
	s_waitcnt vmcnt(0)
	s_cmpk_gt_u32 s30, 0xff
	s_cbranch_scc1 .LBB0_378
	s_barrier

.LBB0_400:
	s_add_u32 s16, s14, 0x100
	s_addc_u32 s17, s15, 0
	s_add_i32 s49, 0, 0x10000
	s_cmp_eq_u32 s48, 40
	s_cselect_b32 s21, s7, s17
	s_cselect_b32 s20, s6, s16
	s_cselect_b32 s19, s9, s47
	s_cselect_b32 s18, s8, s46
	v_lshl_add_u64 v[162:163], s[14:15], 0, v[138:139]
	s_add_i32 m0, s34, 0xc000
	ds_read_b128 v[158:161], v166
	ds_read_b128 v[168:171], v166 offset:1024
	ds_read_b128 v[172:175], v166 offset:2048
	ds_read_b128 v[190:193], v166 offset:3072
	ds_read_b128 v[194:197], v166 offset:4096
	ds_read_b128 v[198:201], v166 offset:5120
	ds_read_b128 v[202:205], v166 offset:6144
	ds_read_b128 v[206:209], v166 offset:7168
	global_load_lds_dwordx4 v[162:163], off
	v_lshl_add_u64 v[162:163], s[14:15], 0, v[140:141]
	s_add_i32 m0, s34, 0xe000
	s_nop 0
	global_load_lds_dwordx4 v[162:163], off
	s_waitcnt lgkmcnt(8)
	s_barrier
	s_waitcnt lgkmcnt(0)
	s_waitcnt lgkmcnt(0)
	v_mfma_f32_16x16x32_bf16 v[126:129], v[142:145], v[158:161], v[126:129]
	v_mfma_f32_16x16x32_bf16 v[122:125], v[150:153], v[158:161], v[122:125]
	v_mfma_f32_16x16x32_bf16 v[110:113], v[142:145], v[172:175], v[110:113]
	v_mfma_f32_16x16x32_bf16 v[106:109], v[150:153], v[172:175], v[106:109]
	v_mfma_f32_16x16x32_bf16 v[94:97], v[142:145], v[194:197], v[94:97]
	v_mfma_f32_16x16x32_bf16 v[90:93], v[150:153], v[194:197], v[90:93]
	v_mfma_f32_16x16x32_bf16 v[78:81], v[142:145], v[202:205], v[78:81]
	v_mfma_f32_16x16x32_bf16 v[74:77], v[150:153], v[202:205], v[74:77]
	v_mfma_f32_16x16x32_bf16 v[126:129], v[146:149], v[168:171], v[126:129]
	v_mfma_f32_16x16x32_bf16 v[122:125], v[154:157], v[168:171], v[122:125]
	v_mfma_f32_16x16x32_bf16 v[110:113], v[146:149], v[190:193], v[110:113]
	v_mfma_f32_16x16x32_bf16 v[106:109], v[154:157], v[190:193], v[106:109]
	v_mfma_f32_16x16x32_bf16 v[94:97], v[146:149], v[198:201], v[94:97]
	v_mfma_f32_16x16x32_bf16 v[90:93], v[154:157], v[198:201], v[90:93]
	v_mfma_f32_16x16x32_bf16 v[78:81], v[146:149], v[206:209], v[78:81]
	v_mfma_f32_16x16x32_bf16 v[74:77], v[154:157], v[206:209], v[74:77]
	s_barrier
	s_add_i32 s50, 0, 0x14000
	v_add_u32_e32 v162, s50, v164
	s_add_i32 s14, s49, s33
	ds_read_b128 v[210:213], v162
	ds_read_b128 v[214:217], v162 offset:1024
	ds_read_b128 v[218:221], v162 offset:2048
	ds_read_b128 v[222:225], v162 offset:3072
	s_add_u32 s64, s18, 0x80
	s_addc_u32 s65, s19, 0
	s_mov_b32 m0, s14
	s_nop 0
	global_load_lds_dwordx4 v132, s[18:19]
	s_add_i32 m0, s14, 0x2000
	s_nop 0
	global_load_lds_dwordx4 v136, s[18:19]
	s_barrier
	s_waitcnt lgkmcnt(0)
	s_waitcnt lgkmcnt(0)
	v_mfma_f32_16x16x32_bf16 v[118:121], v[210:213], v[158:161], v[118:121]
	v_mfma_f32_16x16x32_bf16 v[114:117], v[218:221], v[158:161], v[114:117]
	v_mfma_f32_16x16x32_bf16 v[102:105], v[210:213], v[172:175], v[102:105]
	v_mfma_f32_16x16x32_bf16 v[98:101], v[218:221], v[172:175], v[98:101]
	v_mfma_f32_16x16x32_bf16 v[86:89], v[210:213], v[194:197], v[86:89]
	v_mfma_f32_16x16x32_bf16 v[82:85], v[218:221], v[194:197], v[82:85]
	v_mfma_f32_16x16x32_bf16 v[70:73], v[210:213], v[202:205], v[70:73]
	v_mfma_f32_16x16x32_bf16 v[66:69], v[218:221], v[202:205], v[66:69]
	v_mfma_f32_16x16x32_bf16 v[118:121], v[214:217], v[168:171], v[118:121]
	v_mfma_f32_16x16x32_bf16 v[114:117], v[222:225], v[168:171], v[114:117]
	v_mfma_f32_16x16x32_bf16 v[102:105], v[214:217], v[190:193], v[102:105]
	v_mfma_f32_16x16x32_bf16 v[98:101], v[222:225], v[190:193], v[98:101]
	v_mfma_f32_16x16x32_bf16 v[86:89], v[214:217], v[198:201], v[86:89]
	v_mfma_f32_16x16x32_bf16 v[82:85], v[222:225], v[198:201], v[82:85]
	v_mfma_f32_16x16x32_bf16 v[70:73], v[214:217], v[206:209], v[70:73]
	v_mfma_f32_16x16x32_bf16 v[66:69], v[222:225], v[206:209], v[66:69]
	s_barrier
	s_mov_b32 m0, s34
	s_add_u32 s62, s20, 0x80
	s_addc_u32 s63, s21, 0
	ds_read_b128 v[158:161], v166 offset:16384
	ds_read_b128 v[168:171], v166 offset:17408
	ds_read_b128 v[172:175], v166 offset:18432
	ds_read_b128 v[190:193], v166 offset:19456
	ds_read_b128 v[194:197], v166 offset:20480
	ds_read_b128 v[198:201], v166 offset:21504
	ds_read_b128 v[202:205], v166 offset:22528
	ds_read_b128 v[206:209], v166 offset:23552
	global_load_lds_dwordx4 v130, s[20:21]
	s_mov_b32 m0, s35
	s_nop 0
	global_load_lds_dwordx4 v134, s[20:21]
	s_waitcnt vmcnt(10)
	s_barrier
	s_waitcnt lgkmcnt(0)
	s_waitcnt lgkmcnt(0)
	v_mfma_f32_16x16x32_bf16 v[62:65], v[142:145], v[158:161], v[62:65]
	v_mfma_f32_16x16x32_bf16 v[58:61], v[150:153], v[158:161], v[58:61]
	v_mfma_f32_16x16x32_bf16 v[46:49], v[142:145], v[172:175], v[46:49]
	v_mfma_f32_16x16x32_bf16 v[42:45], v[150:153], v[172:175], v[42:45]
	v_mfma_f32_16x16x32_bf16 v[30:33], v[142:145], v[194:197], v[30:33]
	v_mfma_f32_16x16x32_bf16 v[26:29], v[150:153], v[194:197], v[26:29]
	v_mfma_f32_16x16x32_bf16 v[14:17], v[142:145], v[202:205], v[14:17]
	v_mfma_f32_16x16x32_bf16 v[10:13], v[150:153], v[202:205], v[10:13]
	v_mfma_f32_16x16x32_bf16 v[62:65], v[146:149], v[168:171], v[62:65]
	v_mfma_f32_16x16x32_bf16 v[58:61], v[154:157], v[168:171], v[58:61]
	v_mfma_f32_16x16x32_bf16 v[46:49], v[146:149], v[190:193], v[46:49]
	v_mfma_f32_16x16x32_bf16 v[42:45], v[154:157], v[190:193], v[42:45]
	v_mfma_f32_16x16x32_bf16 v[30:33], v[146:149], v[198:201], v[30:33]
	v_mfma_f32_16x16x32_bf16 v[26:29], v[154:157], v[198:201], v[26:29]
	v_mfma_f32_16x16x32_bf16 v[14:17], v[146:149], v[206:209], v[14:17]
	v_mfma_f32_16x16x32_bf16 v[10:13], v[154:157], v[206:209], v[10:13]
	s_barrier
	v_add_u32_e32 v154, 0x18000, v164
	ds_read_b128 v[142:145], v154
	ds_read_b128 v[146:149], v154 offset:1024
	ds_read_b128 v[150:153], v154 offset:2048
	ds_read_b128 v[154:157], v154 offset:3072
	s_add_u32 s14, s18, 0xb0000
	s_addc_u32 s15, s19, 0
	s_add_i32 s49, s50, s33
	s_mov_b32 m0, s49
	s_nop 0
	global_load_lds_dwordx4 v132, s[14:15]
	s_add_i32 m0, s49, 0x2000
	s_nop 0
	global_load_lds_dwordx4 v136, s[14:15]
	s_waitcnt vmcnt(6)
	s_barrier
	v_mfma_f32_16x16x32_bf16 v[54:57], v[210:213], v[158:161], v[54:57]
	v_mfma_f32_16x16x32_bf16 v[50:53], v[218:221], v[158:161], v[50:53]
	v_mfma_f32_16x16x32_bf16 v[38:41], v[210:213], v[172:175], v[38:41]
	v_mfma_f32_16x16x32_bf16 v[34:37], v[218:221], v[172:175], v[34:37]
	v_mfma_f32_16x16x32_bf16 v[22:25], v[210:213], v[194:197], v[22:25]
	v_mfma_f32_16x16x32_bf16 v[18:21], v[218:221], v[194:197], v[18:21]
	v_mfma_f32_16x16x32_bf16 v[6:9], v[210:213], v[202:205], v[6:9]
	v_mfma_f32_16x16x32_bf16 v[2:5], v[218:221], v[202:205], v[2:5]
	v_mfma_f32_16x16x32_bf16 v[54:57], v[214:217], v[168:171], v[54:57]
	v_mfma_f32_16x16x32_bf16 v[50:53], v[222:225], v[168:171], v[50:53]
	v_mfma_f32_16x16x32_bf16 v[38:41], v[214:217], v[190:193], v[38:41]
	v_mfma_f32_16x16x32_bf16 v[34:37], v[222:225], v[190:193], v[34:37]
	v_mfma_f32_16x16x32_bf16 v[22:25], v[214:217], v[198:201], v[22:25]
	v_mfma_f32_16x16x32_bf16 v[18:21], v[222:225], v[198:201], v[18:21]
	v_mfma_f32_16x16x32_bf16 v[6:9], v[214:217], v[206:209], v[6:9]
	v_mfma_f32_16x16x32_bf16 v[2:5], v[222:225], v[206:209], v[2:5]
	s_barrier
	s_add_i32 s49, 0, 0x18000
	s_add_u32 s14, s20, 0xb8000
	s_addc_u32 s15, s21, 0
	s_mov_b32 m0, s36
	ds_read_b128 v[158:161], v166 offset:32768
	ds_read_b128 v[168:171], v166 offset:33792
	ds_read_b128 v[172:175], v166 offset:34816
	ds_read_b128 v[190:193], v166 offset:35840
	ds_read_b128 v[194:197], v166 offset:36864
	ds_read_b128 v[198:201], v166 offset:37888
	ds_read_b128 v[202:205], v166 offset:38912
	ds_read_b128 v[206:209], v166 offset:39936
	global_load_lds_dwordx4 v130, s[14:15]
	s_mov_b32 m0, s37
	s_nop 0
	global_load_lds_dwordx4 v134, s[14:15]
	s_waitcnt lgkmcnt(8)
	s_barrier
	s_waitcnt lgkmcnt(0)
	s_waitcnt lgkmcnt(0)
	v_mfma_f32_16x16x32_bf16 v[126:129], v[142:145], v[158:161], v[126:129]
	v_mfma_f32_16x16x32_bf16 v[122:125], v[150:153], v[158:161], v[122:125]
	v_mfma_f32_16x16x32_bf16 v[110:113], v[142:145], v[172:175], v[110:113]
	v_mfma_f32_16x16x32_bf16 v[106:109], v[150:153], v[172:175], v[106:109]
	v_mfma_f32_16x16x32_bf16 v[94:97], v[142:145], v[194:197], v[94:97]
	v_mfma_f32_16x16x32_bf16 v[90:93], v[150:153], v[194:197], v[90:93]
	v_mfma_f32_16x16x32_bf16 v[78:81], v[142:145], v[202:205], v[78:81]
	v_mfma_f32_16x16x32_bf16 v[74:77], v[150:153], v[202:205], v[74:77]
	v_mfma_f32_16x16x32_bf16 v[126:129], v[146:149], v[168:171], v[126:129]
	v_mfma_f32_16x16x32_bf16 v[122:125], v[154:157], v[168:171], v[122:125]
	v_mfma_f32_16x16x32_bf16 v[110:113], v[146:149], v[190:193], v[110:113]
	v_mfma_f32_16x16x32_bf16 v[106:109], v[154:157], v[190:193], v[106:109]
	v_mfma_f32_16x16x32_bf16 v[94:97], v[146:149], v[198:201], v[94:97]
	v_mfma_f32_16x16x32_bf16 v[90:93], v[154:157], v[198:201], v[90:93]
	v_mfma_f32_16x16x32_bf16 v[78:81], v[146:149], v[206:209], v[78:81]
	v_mfma_f32_16x16x32_bf16 v[74:77], v[154:157], v[206:209], v[74:77]
	s_barrier
	s_add_i32 s20, 0, 0x1c000
	s_add_i32 s14, s49, s33
	v_add_u32_e32 v167, s20, v164
	s_mov_b32 m0, s14
	ds_read_b128 v[210:213], v167
	ds_read_b128 v[214:217], v167 offset:1024
	ds_read_b128 v[218:221], v167 offset:2048
	ds_read_b128 v[222:225], v167 offset:3072
	global_load_lds_dwordx4 v132, s[64:65]
	s_add_i32 m0, s14, 0x2000
	s_nop 0
	global_load_lds_dwordx4 v136, s[64:65]
	s_barrier
	s_waitcnt lgkmcnt(0)
	s_waitcnt lgkmcnt(0)
	v_mfma_f32_16x16x32_bf16 v[118:121], v[210:213], v[158:161], v[118:121]
	v_mfma_f32_16x16x32_bf16 v[114:117], v[218:221], v[158:161], v[114:117]
	v_mfma_f32_16x16x32_bf16 v[102:105], v[210:213], v[172:175], v[102:105]
	v_mfma_f32_16x16x32_bf16 v[98:101], v[218:221], v[172:175], v[98:101]
	v_mfma_f32_16x16x32_bf16 v[86:89], v[210:213], v[194:197], v[86:89]
	v_mfma_f32_16x16x32_bf16 v[82:85], v[218:221], v[194:197], v[82:85]
	v_mfma_f32_16x16x32_bf16 v[70:73], v[210:213], v[202:205], v[70:73]
	v_mfma_f32_16x16x32_bf16 v[66:69], v[218:221], v[202:205], v[66:69]
	v_mfma_f32_16x16x32_bf16 v[118:121], v[214:217], v[168:171], v[118:121]
	v_mfma_f32_16x16x32_bf16 v[114:117], v[222:225], v[168:171], v[114:117]
	v_mfma_f32_16x16x32_bf16 v[102:105], v[214:217], v[190:193], v[102:105]
	v_mfma_f32_16x16x32_bf16 v[98:101], v[222:225], v[190:193], v[98:101]
	v_mfma_f32_16x16x32_bf16 v[86:89], v[214:217], v[198:201], v[86:89]
	v_mfma_f32_16x16x32_bf16 v[82:85], v[222:225], v[198:201], v[82:85]
	v_mfma_f32_16x16x32_bf16 v[70:73], v[214:217], v[206:209], v[70:73]
	v_mfma_f32_16x16x32_bf16 v[66:69], v[222:225], v[206:209], v[66:69]
	s_barrier
	s_mov_b32 m0, s38
	ds_read_b128 v[158:161], v166 offset:49152
	ds_read_b128 v[168:171], v166 offset:50176
	ds_read_b128 v[172:175], v166 offset:51200
	ds_read_b128 v[190:193], v166 offset:52224
	ds_read_b128 v[194:197], v166 offset:53248
	ds_read_b128 v[198:201], v166 offset:54272
	ds_read_b128 v[202:205], v166 offset:55296
	ds_read_b128 v[206:209], v166 offset:56320
	global_load_lds_dwordx4 v130, s[62:63]
	s_mov_b32 m0, s39
	s_nop 0
	global_load_lds_dwordx4 v134, s[62:63]
	s_waitcnt vmcnt(10)
	s_barrier
	s_waitcnt lgkmcnt(0)
	s_waitcnt lgkmcnt(0)
	v_mfma_f32_16x16x32_bf16 v[62:65], v[142:145], v[158:161], v[62:65]
	v_mfma_f32_16x16x32_bf16 v[58:61], v[150:153], v[158:161], v[58:61]
	v_mfma_f32_16x16x32_bf16 v[46:49], v[142:145], v[172:175], v[46:49]
	v_mfma_f32_16x16x32_bf16 v[42:45], v[150:153], v[172:175], v[42:45]
	v_mfma_f32_16x16x32_bf16 v[30:33], v[142:145], v[194:197], v[30:33]
	v_mfma_f32_16x16x32_bf16 v[26:29], v[150:153], v[194:197], v[26:29]
	v_mfma_f32_16x16x32_bf16 v[14:17], v[142:145], v[202:205], v[14:17]
	v_mfma_f32_16x16x32_bf16 v[10:13], v[150:153], v[202:205], v[10:13]
	v_mfma_f32_16x16x32_bf16 v[62:65], v[146:149], v[168:171], v[62:65]
	v_mfma_f32_16x16x32_bf16 v[58:61], v[154:157], v[168:171], v[58:61]
	v_mfma_f32_16x16x32_bf16 v[46:49], v[146:149], v[190:193], v[46:49]
	v_mfma_f32_16x16x32_bf16 v[42:45], v[154:157], v[190:193], v[42:45]
	v_mfma_f32_16x16x32_bf16 v[30:33], v[146:149], v[198:201], v[30:33]
	v_mfma_f32_16x16x32_bf16 v[26:29], v[154:157], v[198:201], v[26:29]
	v_mfma_f32_16x16x32_bf16 v[14:17], v[146:149], v[206:209], v[14:17]
	v_mfma_f32_16x16x32_bf16 v[10:13], v[154:157], v[206:209], v[10:13]
	s_barrier
	v_add_u32_e32 v154, 0x10000, v164
	ds_read_b128 v[142:145], v154
	ds_read_b128 v[146:149], v154 offset:1024
	ds_read_b128 v[150:153], v154 offset:2048
	ds_read_b128 v[154:157], v154 offset:3072
	s_add_u32 s14, s18, 0xb0080
	s_addc_u32 s15, s19, 0
	s_add_i32 s18, s20, s33
	s_mov_b32 m0, s18
	s_nop 0
	global_load_lds_dwordx4 v132, s[14:15]
	s_add_i32 m0, s18, 0x2000
	s_nop 0
	global_load_lds_dwordx4 v136, s[14:15]
	s_waitcnt vmcnt(6)
	s_barrier
	v_mfma_f32_16x16x32_bf16 v[54:57], v[210:213], v[158:161], v[54:57]
	v_mfma_f32_16x16x32_bf16 v[50:53], v[218:221], v[158:161], v[50:53]
	v_mfma_f32_16x16x32_bf16 v[38:41], v[210:213], v[172:175], v[38:41]
	v_mfma_f32_16x16x32_bf16 v[34:37], v[218:221], v[172:175], v[34:37]
	v_mfma_f32_16x16x32_bf16 v[22:25], v[210:213], v[194:197], v[22:25]
	v_mfma_f32_16x16x32_bf16 v[18:21], v[218:221], v[194:197], v[18:21]
	v_mfma_f32_16x16x32_bf16 v[6:9], v[210:213], v[202:205], v[6:9]
	v_mfma_f32_16x16x32_bf16 v[2:5], v[218:221], v[202:205], v[2:5]
	v_mfma_f32_16x16x32_bf16 v[54:57], v[214:217], v[168:171], v[54:57]
	v_mfma_f32_16x16x32_bf16 v[50:53], v[222:225], v[168:171], v[50:53]
	v_mfma_f32_16x16x32_bf16 v[38:41], v[214:217], v[190:193], v[38:41]
	v_mfma_f32_16x16x32_bf16 v[34:37], v[222:225], v[190:193], v[34:37]
	v_mfma_f32_16x16x32_bf16 v[22:25], v[214:217], v[198:201], v[22:25]
	v_mfma_f32_16x16x32_bf16 v[18:21], v[222:225], v[198:201], v[18:21]
	v_mfma_f32_16x16x32_bf16 v[6:9], v[214:217], v[206:209], v[6:9]
	v_mfma_f32_16x16x32_bf16 v[2:5], v[222:225], v[206:209], v[2:5]
	s_barrier
	s_add_i32 s48, s48, 2
	s_add_u32 s46, s46, 0x100
	s_addc_u32 s47, s47, 0
	s_cmp_gt_u32 s48, 41
	s_mov_b64 s[14:15], s[16:17]
	s_cbranch_scc0 .LBB0_400
	s_waitcnt lgkmcnt(0)
	s_ashr_i32 s14, s44, 5
	v_lshl_or_b32 v176, s45, 8, v165
	s_mul_hi_i32 s15, s14, 0x9000
	s_mul_i32 s14, s14, 0x9000
	s_add_u32 s14, s26, s14
	v_ashrrev_i32_e32 v177, 31, v176
	s_addc_u32 s15, s27, s15
	v_lshlrev_b64 v[158:159], 2, v[176:177]
	v_lshl_add_u64 v[160:161], s[14:15], 0, v[158:159]
	global_load_dwordx4 v[142:145], v[160:161], off offset:16
	global_load_dwordx4 v[146:149], v[160:161], off
	v_lshl_add_u32 v162, s44, 8, v1
	v_ashrrev_i32_e32 v163, 31, v162
	v_lshl_add_u32 v131, v162, 12, v158
	global_load_dwordx4 v[188:191], v131, s[2:3] offset:16
	global_load_dwordx4 v[192:195], v131, s[2:3]
	global_load_dwordx4 v[196:199], v131, s[2:3] offset:528
	global_load_dwordx4 v[200:203], v131, s[2:3] offset:512
	v_add_u32_e32 v131, 0x10000, v131
	global_load_dwordx4 v[204:207], v131, s[2:3] offset:16
	global_load_dwordx4 v[208:211], v131, s[2:3]
	global_load_dwordx4 v[212:215], v131, s[2:3] offset:528
	global_load_dwordx4 v[216:219], v131, s[2:3] offset:512
	v_add_u32_e32 v131, 0x10000, v131
	global_load_dwordx4 v[220:223], v131, s[2:3] offset:16
	global_load_dwordx4 v[224:227], v131, s[2:3]
	global_load_dwordx4 v[228:231], v131, s[2:3] offset:528
	global_load_dwordx4 v[236:239], v131, s[2:3] offset:512
	v_add_u32_e32 v131, 0x10000, v131
	global_load_dwordx4 v[246:249], v131, s[2:3] offset:16
	global_load_dwordx4 v[250:253], v131, s[2:3]
	v_mov_b32_e32 v133, v131
	s_mov_b64 s[14:15], 0x80000
	s_and_b64 vcc, exec, s[4:5]
	s_mov_b32 s45, s42
	s_mov_b32 s44, s43
	s_mov_b64 s[16:17], s[8:9]
	s_waitcnt vmcnt(14)
	v_pk_add_f32 v[144:145], v[144:145], 1.0 op_sel_hi:[1,0]
	v_pk_add_f32 v[148:149], v[148:149], 1.0 op_sel_hi:[1,0]
	v_pk_add_f32 v[146:147], v[146:147], 1.0 op_sel_hi:[1,0]
	v_pk_add_f32 v[142:143], v[142:143], 1.0 op_sel_hi:[1,0]
	v_pk_mul_f32 v[150:151], v[148:149], 0.5 op_sel_hi:[1,0]
	v_pk_mul_f32 v[152:153], v[146:147], 0.5 op_sel_hi:[1,0]
	v_pk_mul_f32 v[154:155], v[144:145], 0.5 op_sel_hi:[1,0]
	v_pk_mul_f32 v[156:157], v[142:143], 0.5 op_sel_hi:[1,0]
	global_load_dwordx4 v[146:149], v[160:161], off offset:528
	global_load_dwordx4 v[142:145], v[160:161], off offset:512
	s_waitcnt vmcnt(0)
	v_pk_add_f32 v[148:149], v[148:149], 1.0 op_sel_hi:[1,0]
	v_pk_add_f32 v[144:145], v[144:145], 1.0 op_sel_hi:[1,0]
	v_pk_add_f32 v[160:161], v[142:143], 1.0 op_sel_hi:[1,0]
	v_pk_mul_f32 v[142:143], v[144:145], 0.5 op_sel_hi:[1,0]
	v_pk_mul_f32 v[144:145], v[160:161], 0.5 op_sel_hi:[1,0]
	v_pk_add_f32 v[160:161], v[146:147], 1.0 op_sel_hi:[1,0]
	v_pk_mul_f32 v[146:147], v[148:149], 0.5 op_sel_hi:[1,0]
	v_pk_mul_f32 v[148:149], v[160:161], 0.5 op_sel_hi:[1,0]
	v_lshlrev_b64 v[160:161], 12, v[162:163]
	v_lshl_add_u64 v[168:169], s[2:3], 0, v[160:161]
	v_lshl_add_u64 v[186:187], v[168:169], 0, v[158:159]
	v_mov_b32_e32 v168, v188
	v_mov_b32_e32 v169, v189
	v_mov_b32_e32 v170, v190
	v_mov_b32_e32 v171, v191
	v_mov_b32_e32 v172, v192
	v_mov_b32_e32 v173, v193
	v_mov_b32_e32 v174, v194
	v_mov_b32_e32 v175, v195
	global_load_dwordx4 v[188:191], v133, s[2:3] offset:528
	global_load_dwordx4 v[192:195], v133, s[2:3] offset:512
	v_pk_fma_f32 v[122:123], v[122:123], v[156:157], v[168:169]
	v_pk_fma_f32 v[128:129], v[128:129], v[150:151], v[174:175]
	v_pk_fma_f32 v[126:127], v[126:127], v[152:153], v[172:173]
	v_pk_fma_f32 v[170:171], v[124:125], v[154:155], v[170:171]
	v_cvt_pk_bf16_f32 v124, v126, v127
	v_cvt_pk_bf16_f32 v125, v128, v129
	v_cvt_pk_bf16_f32 v126, v122, v123
	v_lshl_add_u64 v[128:129], s[12:13], 0, v[160:161]
	v_lshlrev_b64 v[122:123], 1, v[176:177]
	v_cvt_pk_bf16_f32 v127, v170, v171
	v_lshl_add_u64 v[128:129], v[128:129], 0, v[122:123]
	global_store_dwordx4 v[128:129], v[124:127], off offset:2048
	s_nop 1
	v_mov_b32_e32 v124, v196
	v_mov_b32_e32 v125, v197
	v_mov_b32_e32 v126, v198
	v_mov_b32_e32 v127, v199
	s_nop 0
	v_mov_b32_e32 v168, v200
	v_mov_b32_e32 v169, v201
	v_mov_b32_e32 v170, v202
	v_mov_b32_e32 v171, v203
	v_add_u32_e32 v133, 0x50000, v133
	global_load_dwordx4 v[196:199], v133, s[2:3] offset:16
	global_load_dwordx4 v[200:203], v133, s[2:3]
	v_pk_fma_f32 v[126:127], v[116:117], v[146:147], v[126:127]
	v_pk_fma_f32 v[120:121], v[120:121], v[142:143], v[170:171]
	v_pk_fma_f32 v[118:119], v[118:119], v[144:145], v[168:169]
	v_pk_fma_f32 v[116:117], v[114:115], v[148:149], v[124:125]
	v_cvt_pk_bf16_f32 v114, v118, v119
	v_cvt_pk_bf16_f32 v115, v120, v121
	v_cvt_pk_bf16_f32 v116, v116, v117
	v_cvt_pk_bf16_f32 v117, v126, v127
	global_store_dwordx4 v[128:129], v[114:117], off offset:2304
	s_nop 1
	v_or_b32_e32 v114, 16, v162
	v_ashrrev_i32_e32 v115, 31, v114
	v_lshlrev_b64 v[124:125], 12, v[114:115]
	v_lshl_add_u64 v[114:115], s[2:3], 0, v[124:125]
	v_lshl_add_u64 v[126:127], v[114:115], 0, v[158:159]
	v_mov_b32_e32 v114, v204
	v_mov_b32_e32 v115, v205
	v_mov_b32_e32 v116, v206
	v_mov_b32_e32 v117, v207
	v_mov_b32_e32 v118, v208
	v_mov_b32_e32 v119, v209
	v_mov_b32_e32 v120, v210
	v_mov_b32_e32 v121, v211
	global_load_dwordx4 v[204:207], v133, s[2:3] offset:528
	global_load_dwordx4 v[208:211], v133, s[2:3] offset:512
	v_pk_fma_f32 v[116:117], v[108:109], v[154:155], v[116:117]
	v_pk_fma_f32 v[110:111], v[110:111], v[152:153], v[118:119]
	v_pk_fma_f32 v[112:113], v[112:113], v[150:151], v[120:121]
	v_pk_fma_f32 v[108:109], v[106:107], v[156:157], v[114:115]
	v_cvt_pk_bf16_f32 v106, v110, v111
	v_lshl_add_u64 v[110:111], s[12:13], 0, v[124:125]
	v_cvt_pk_bf16_f32 v107, v112, v113
	v_cvt_pk_bf16_f32 v108, v108, v109
	v_cvt_pk_bf16_f32 v109, v116, v117
	v_lshl_add_u64 v[114:115], v[110:111], 0, v[122:123]
	global_store_dwordx4 v[114:115], v[106:109], off offset:2048
	s_nop 1
	v_mov_b32_e32 v106, v212
	v_mov_b32_e32 v107, v213
	v_mov_b32_e32 v108, v214
	v_mov_b32_e32 v109, v215
	s_nop 0
	v_mov_b32_e32 v110, v216
	v_mov_b32_e32 v111, v217
	v_mov_b32_e32 v112, v218
	v_mov_b32_e32 v113, v219
	v_add_u32_e32 v133, 0x10000, v133
	global_load_dwordx4 v[212:215], v133, s[2:3] offset:16
	global_load_dwordx4 v[216:219], v133, s[2:3]
	v_pk_fma_f32 v[108:109], v[100:101], v[146:147], v[108:109]
	v_pk_fma_f32 v[104:105], v[104:105], v[142:143], v[112:113]
	v_pk_fma_f32 v[102:103], v[102:103], v[144:145], v[110:111]
	v_pk_fma_f32 v[100:101], v[98:99], v[148:149], v[106:107]
	v_cvt_pk_bf16_f32 v98, v102, v103
	v_cvt_pk_bf16_f32 v99, v104, v105
	v_cvt_pk_bf16_f32 v100, v100, v101
	v_cvt_pk_bf16_f32 v101, v108, v109
	global_store_dwordx4 v[114:115], v[98:101], off offset:2304
	s_nop 1
	v_or_b32_e32 v98, 32, v162
	v_ashrrev_i32_e32 v99, 31, v98
	v_lshlrev_b64 v[106:107], 12, v[98:99]
	v_lshl_add_u64 v[98:99], s[2:3], 0, v[106:107]
	v_lshl_add_u64 v[108:109], v[98:99], 0, v[158:159]
	v_mov_b32_e32 v98, v220
	v_mov_b32_e32 v99, v221
	v_mov_b32_e32 v100, v222
	v_mov_b32_e32 v101, v223
	v_mov_b32_e32 v102, v224
	v_mov_b32_e32 v103, v225
	v_mov_b32_e32 v104, v226
	v_mov_b32_e32 v105, v227
	global_load_dwordx4 v[220:223], v133, s[2:3] offset:528
	global_load_dwordx4 v[224:227], v133, s[2:3] offset:512
	v_pk_fma_f32 v[100:101], v[92:93], v[154:155], v[100:101]
	v_pk_fma_f32 v[94:95], v[94:95], v[152:153], v[102:103]
	v_pk_fma_f32 v[96:97], v[96:97], v[150:151], v[104:105]
	v_pk_fma_f32 v[92:93], v[90:91], v[156:157], v[98:99]
	v_cvt_pk_bf16_f32 v90, v94, v95
	v_lshl_add_u64 v[94:95], s[12:13], 0, v[106:107]
	v_cvt_pk_bf16_f32 v91, v96, v97
	v_cvt_pk_bf16_f32 v92, v92, v93
	v_cvt_pk_bf16_f32 v93, v100, v101
	v_lshl_add_u64 v[98:99], v[94:95], 0, v[122:123]
	global_store_dwordx4 v[98:99], v[90:93], off offset:2048
	s_nop 1
	v_mov_b32_e32 v90, v228
	v_mov_b32_e32 v91, v229
	v_mov_b32_e32 v92, v230
	v_mov_b32_e32 v93, v231
	s_nop 0
	v_mov_b32_e32 v94, v236
	v_mov_b32_e32 v95, v237
	v_mov_b32_e32 v96, v238
	v_mov_b32_e32 v97, v239
	v_add_u32_e32 v133, 0x10000, v133
	global_load_dwordx4 v[228:231], v133, s[2:3] offset:16
	global_load_dwordx4 v[236:239], v133, s[2:3]
	v_pk_fma_f32 v[92:93], v[84:85], v[146:147], v[92:93]
	v_pk_fma_f32 v[88:89], v[88:89], v[142:143], v[96:97]
	v_pk_fma_f32 v[86:87], v[86:87], v[144:145], v[94:95]
	v_pk_fma_f32 v[84:85], v[82:83], v[148:149], v[90:91]
	v_cvt_pk_bf16_f32 v82, v86, v87
	v_cvt_pk_bf16_f32 v83, v88, v89
	v_cvt_pk_bf16_f32 v84, v84, v85
	v_cvt_pk_bf16_f32 v85, v92, v93
	global_store_dwordx4 v[98:99], v[82:85], off offset:2304
	s_nop 1
	v_or_b32_e32 v82, 48, v162
	v_ashrrev_i32_e32 v83, 31, v82
	v_lshlrev_b64 v[90:91], 12, v[82:83]
	v_lshl_add_u64 v[82:83], s[2:3], 0, v[90:91]
	v_lshl_add_u64 v[92:93], v[82:83], 0, v[158:159]
	v_mov_b32_e32 v82, v246
	v_mov_b32_e32 v83, v247
	v_mov_b32_e32 v84, v248
	v_mov_b32_e32 v85, v249
	v_mov_b32_e32 v86, v250
	v_mov_b32_e32 v87, v251
	v_mov_b32_e32 v88, v252
	v_mov_b32_e32 v89, v253
	global_load_dwordx4 v[246:249], v133, s[2:3] offset:528
	global_load_dwordx4 v[250:253], v133, s[2:3] offset:512
	v_pk_fma_f32 v[84:85], v[76:77], v[154:155], v[84:85]
	v_pk_fma_f32 v[78:79], v[78:79], v[152:153], v[86:87]
	v_pk_fma_f32 v[80:81], v[80:81], v[150:151], v[88:89]
	v_pk_fma_f32 v[76:77], v[74:75], v[156:157], v[82:83]
	v_cvt_pk_bf16_f32 v74, v78, v79
	v_lshl_add_u64 v[78:79], s[12:13], 0, v[90:91]
	v_cvt_pk_bf16_f32 v75, v80, v81
	v_cvt_pk_bf16_f32 v76, v76, v77
	v_cvt_pk_bf16_f32 v77, v84, v85
	v_lshl_add_u64 v[82:83], v[78:79], 0, v[122:123]
	global_store_dwordx4 v[82:83], v[74:77], off offset:2048
	s_nop 1
	s_waitcnt vmcnt(19)
	v_mov_b32_e32 v74, v188
	v_mov_b32_e32 v75, v189
	v_mov_b32_e32 v76, v190
	v_mov_b32_e32 v77, v191
	s_nop 0
	v_mov_b32_e32 v78, v192
	v_mov_b32_e32 v79, v193
	v_mov_b32_e32 v80, v194
	v_mov_b32_e32 v81, v195
	v_add_u32_e32 v133, 0x10000, v133
	global_load_dwordx4 v[188:191], v133, s[2:3] offset:16
	global_load_dwordx4 v[192:195], v133, s[2:3]
	v_pk_fma_f32 v[76:77], v[68:69], v[146:147], v[76:77]
	v_pk_fma_f32 v[72:73], v[72:73], v[142:143], v[80:81]
	v_pk_fma_f32 v[70:71], v[70:71], v[144:145], v[78:79]
	v_pk_fma_f32 v[68:69], v[66:67], v[148:149], v[74:75]
	v_cvt_pk_bf16_f32 v66, v70, v71
	v_cvt_pk_bf16_f32 v67, v72, v73
	v_cvt_pk_bf16_f32 v68, v68, v69
	v_cvt_pk_bf16_f32 v69, v76, v77
	v_lshl_add_u64 v[74:75], v[160:161], 0, s[14:15]
	global_store_dwordx4 v[82:83], v[66:69], off offset:2304
	s_mov_b64 s[14:15], 0x90000
	s_nop 0
	v_lshl_add_u64 v[66:67], s[2:3], 0, v[74:75]
	v_lshl_add_u64 v[76:77], v[66:67], 0, v[158:159]
	s_waitcnt vmcnt(19)
	v_mov_b32_e32 v66, v196
	v_mov_b32_e32 v67, v197
	v_mov_b32_e32 v68, v198
	v_mov_b32_e32 v69, v199
	v_mov_b32_e32 v70, v200
	v_mov_b32_e32 v71, v201
	v_mov_b32_e32 v72, v202
	v_mov_b32_e32 v73, v203
	global_load_dwordx4 v[196:199], v133, s[2:3] offset:528
	global_load_dwordx4 v[200:203], v133, s[2:3] offset:512
	v_pk_fma_f32 v[68:69], v[60:61], v[154:155], v[68:69]
	v_pk_fma_f32 v[62:63], v[62:63], v[152:153], v[70:71]
	v_pk_fma_f32 v[64:65], v[64:65], v[150:151], v[72:73]
	v_pk_fma_f32 v[60:61], v[58:59], v[156:157], v[66:67]
	v_cvt_pk_bf16_f32 v58, v62, v63
	v_lshl_add_u64 v[62:63], s[12:13], 0, v[74:75]
	v_cvt_pk_bf16_f32 v59, v64, v65
	v_cvt_pk_bf16_f32 v60, v60, v61
	v_cvt_pk_bf16_f32 v61, v68, v69
	v_lshl_add_u64 v[66:67], v[62:63], 0, v[122:123]
	global_store_dwordx4 v[66:67], v[58:61], off offset:2048
	s_nop 1
	s_waitcnt vmcnt(19)
	v_mov_b32_e32 v58, v204
	v_mov_b32_e32 v59, v205
	v_mov_b32_e32 v60, v206
	v_mov_b32_e32 v61, v207
	s_nop 0
	v_mov_b32_e32 v62, v208
	v_mov_b32_e32 v63, v209
	v_mov_b32_e32 v64, v210
	v_mov_b32_e32 v65, v211
	s_nop 0
	v_pk_fma_f32 v[60:61], v[52:53], v[146:147], v[60:61]
	v_pk_fma_f32 v[56:57], v[56:57], v[142:143], v[64:65]
	v_pk_fma_f32 v[54:55], v[54:55], v[144:145], v[62:63]
	v_pk_fma_f32 v[52:53], v[50:51], v[148:149], v[58:59]
	v_cvt_pk_bf16_f32 v50, v54, v55
	v_cvt_pk_bf16_f32 v51, v56, v57
	v_cvt_pk_bf16_f32 v52, v52, v53
	v_cvt_pk_bf16_f32 v53, v60, v61
	v_lshl_add_u64 v[58:59], v[160:161], 0, s[14:15]
	global_store_dwordx4 v[66:67], v[50:53], off offset:2304
	s_mov_b64 s[14:15], 0xa0000
	s_nop 0
	v_lshl_add_u64 v[50:51], s[2:3], 0, v[58:59]
	v_lshl_add_u64 v[60:61], v[50:51], 0, v[158:159]
	s_waitcnt vmcnt(17)
	v_mov_b32_e32 v50, v212
	v_mov_b32_e32 v51, v213
	v_mov_b32_e32 v52, v214
	v_mov_b32_e32 v53, v215
	v_mov_b32_e32 v54, v216
	v_mov_b32_e32 v55, v217
	v_mov_b32_e32 v56, v218
	v_mov_b32_e32 v57, v219
	s_nop 0
	v_pk_fma_f32 v[52:53], v[44:45], v[154:155], v[52:53]
	v_pk_fma_f32 v[46:47], v[46:47], v[152:153], v[54:55]
	v_pk_fma_f32 v[48:49], v[48:49], v[150:151], v[56:57]
	v_pk_fma_f32 v[44:45], v[42:43], v[156:157], v[50:51]
	v_cvt_pk_bf16_f32 v42, v46, v47
	v_lshl_add_u64 v[46:47], s[12:13], 0, v[58:59]
	v_cvt_pk_bf16_f32 v43, v48, v49
	v_cvt_pk_bf16_f32 v44, v44, v45
	v_cvt_pk_bf16_f32 v45, v52, v53
	v_lshl_add_u64 v[50:51], v[46:47], 0, v[122:123]
	global_store_dwordx4 v[50:51], v[42:45], off offset:2048
	s_nop 1
	s_waitcnt vmcnt(15)
	v_mov_b32_e32 v42, v220
	v_mov_b32_e32 v43, v221
	v_mov_b32_e32 v44, v222
	v_mov_b32_e32 v45, v223
	s_nop 0
	v_mov_b32_e32 v46, v224
	v_mov_b32_e32 v47, v225
	v_mov_b32_e32 v48, v226
	v_mov_b32_e32 v49, v227
	s_nop 0
	v_pk_fma_f32 v[44:45], v[36:37], v[146:147], v[44:45]
	v_pk_fma_f32 v[40:41], v[40:41], v[142:143], v[48:49]
	v_pk_fma_f32 v[38:39], v[38:39], v[144:145], v[46:47]
	v_pk_fma_f32 v[36:37], v[34:35], v[148:149], v[42:43]
	v_cvt_pk_bf16_f32 v34, v38, v39
	v_cvt_pk_bf16_f32 v35, v40, v41
	v_cvt_pk_bf16_f32 v36, v36, v37
	v_cvt_pk_bf16_f32 v37, v44, v45
	v_lshl_add_u64 v[42:43], v[160:161], 0, s[14:15]
	global_store_dwordx4 v[50:51], v[34:37], off offset:2304
	s_mov_b64 s[14:15], 0xb0000
	s_nop 0
	v_lshl_add_u64 v[34:35], s[2:3], 0, v[42:43]
	v_lshl_add_u64 v[44:45], v[34:35], 0, v[158:159]
	s_waitcnt vmcnt(13)
	v_mov_b32_e32 v34, v228
	v_mov_b32_e32 v35, v229
	v_mov_b32_e32 v36, v230
	v_mov_b32_e32 v37, v231
	v_mov_b32_e32 v38, v236
	v_mov_b32_e32 v39, v237
	v_mov_b32_e32 v40, v238
	v_mov_b32_e32 v41, v239
	s_nop 0
	v_pk_fma_f32 v[36:37], v[28:29], v[154:155], v[36:37]
	v_pk_fma_f32 v[30:31], v[30:31], v[152:153], v[38:39]
	v_pk_fma_f32 v[32:33], v[32:33], v[150:151], v[40:41]
	v_pk_fma_f32 v[28:29], v[26:27], v[156:157], v[34:35]
	v_cvt_pk_bf16_f32 v26, v30, v31
	v_lshl_add_u64 v[30:31], s[12:13], 0, v[42:43]
	v_cvt_pk_bf16_f32 v27, v32, v33
	v_cvt_pk_bf16_f32 v28, v28, v29
	v_cvt_pk_bf16_f32 v29, v36, v37
	v_lshl_add_u64 v[34:35], v[30:31], 0, v[122:123]
	global_store_dwordx4 v[34:35], v[26:29], off offset:2048
	s_nop 1
	s_waitcnt vmcnt(11)
	v_mov_b32_e32 v26, v246
	v_mov_b32_e32 v27, v247
	v_mov_b32_e32 v28, v248
	v_mov_b32_e32 v29, v249
	s_nop 0
	v_mov_b32_e32 v30, v250
	v_mov_b32_e32 v31, v251
	v_mov_b32_e32 v32, v252
	v_mov_b32_e32 v33, v253
	s_nop 0
	v_pk_fma_f32 v[28:29], v[20:21], v[146:147], v[28:29]
	v_pk_fma_f32 v[24:25], v[24:25], v[142:143], v[32:33]
	v_pk_fma_f32 v[22:23], v[22:23], v[144:145], v[30:31]
	v_pk_fma_f32 v[20:21], v[18:19], v[148:149], v[26:27]
	v_cvt_pk_bf16_f32 v18, v22, v23
	v_cvt_pk_bf16_f32 v19, v24, v25
	v_cvt_pk_bf16_f32 v20, v20, v21
	v_cvt_pk_bf16_f32 v21, v28, v29
	v_lshl_add_u64 v[26:27], v[160:161], 0, s[14:15]
	global_store_dwordx4 v[34:35], v[18:21], off offset:2304
	s_mov_b64 s[14:15], s[6:7]
	s_nop 0
	v_lshl_add_u64 v[18:19], s[2:3], 0, v[26:27]
	v_lshl_add_u64 v[28:29], v[18:19], 0, v[158:159]
	s_waitcnt vmcnt(9)
	v_mov_b32_e32 v18, v188
	v_mov_b32_e32 v19, v189
	v_mov_b32_e32 v20, v190
	v_mov_b32_e32 v21, v191
	v_mov_b32_e32 v22, v192
	v_mov_b32_e32 v23, v193
	v_mov_b32_e32 v24, v194
	v_mov_b32_e32 v25, v195
	s_nop 0
	v_pk_fma_f32 v[20:21], v[12:13], v[154:155], v[20:21]
	v_pk_fma_f32 v[14:15], v[14:15], v[152:153], v[22:23]
	v_pk_fma_f32 v[16:17], v[16:17], v[150:151], v[24:25]
	v_pk_fma_f32 v[12:13], v[10:11], v[156:157], v[18:19]
	v_cvt_pk_bf16_f32 v10, v14, v15
	v_lshl_add_u64 v[14:15], s[12:13], 0, v[26:27]
	v_cvt_pk_bf16_f32 v11, v16, v17
	v_cvt_pk_bf16_f32 v12, v12, v13
	v_cvt_pk_bf16_f32 v13, v20, v21
	v_lshl_add_u64 v[18:19], v[14:15], 0, v[122:123]
	global_store_dwordx4 v[18:19], v[10:13], off offset:2048
	s_nop 1
	s_waitcnt vmcnt(7)
	v_mov_b32_e32 v10, v196
	v_mov_b32_e32 v11, v197
	v_mov_b32_e32 v12, v198
	v_mov_b32_e32 v13, v199
	s_nop 0
	v_mov_b32_e32 v14, v200
	v_mov_b32_e32 v15, v201
	v_mov_b32_e32 v16, v202
	v_mov_b32_e32 v17, v203
	s_nop 0
	v_pk_fma_f32 v[12:13], v[4:5], v[146:147], v[12:13]
	v_pk_fma_f32 v[8:9], v[8:9], v[142:143], v[16:17]
	v_pk_fma_f32 v[6:7], v[6:7], v[144:145], v[14:15]
	v_pk_fma_f32 v[4:5], v[2:3], v[148:149], v[10:11]
	v_cvt_pk_bf16_f32 v2, v6, v7
	v_cvt_pk_bf16_f32 v3, v8, v9
	v_cvt_pk_bf16_f32 v4, v4, v5
	v_cvt_pk_bf16_f32 v5, v12, v13
	global_store_dwordx4 v[18:19], v[2:5], off offset:2304
	s_cbranch_vccz .LBB0_389
	s_waitcnt vmcnt(0)
	s_cmpk_gt_u32 s30, 0xff
	s_cbranch_scc1 .LBB0_404
	s_barrier

.LBB0_1408:
	s_add_u32 s16, s14, s6
	s_addc_u32 s17, s15, s7
	s_add_u32 s16, s16, 0x100
	s_addc_u32 s17, s17, 0
	s_add_u32 s48, s45, s6
	s_addc_u32 s49, s46, s7
	s_add_i32 s50, 0, 0x10000
	s_cmpk_eq_i32 s6, 0xf00
	s_cselect_b32 s19, s11, s17
	s_cselect_b32 s18, s10, s16
	s_cselect_b32 s17, s3, s49
	s_cselect_b32 s16, s44, s48
	v_lshl_add_u64 v[162:163], v[142:143], 0, s[6:7]
	s_add_i32 m0, s30, 0xc000
	ds_read_b128 v[168:171], v166
	ds_read_b128 v[172:175], v166 offset:1024
	ds_read_b128 v[186:189], v166 offset:2048
	ds_read_b128 v[190:193], v166 offset:3072
	ds_read_b128 v[194:197], v166 offset:4096
	ds_read_b128 v[198:201], v166 offset:5120
	ds_read_b128 v[202:205], v166 offset:6144
	ds_read_b128 v[206:209], v166 offset:7168
	global_load_lds_dwordx4 v[162:163], off
	v_lshl_add_u64 v[162:163], v[144:145], 0, s[6:7]
	s_add_i32 m0, s30, 0xe000
	s_nop 0
	global_load_lds_dwordx4 v[162:163], off
	s_waitcnt lgkmcnt(8)
	s_barrier
	s_waitcnt lgkmcnt(0)
	s_waitcnt lgkmcnt(0)
	v_mfma_f32_16x16x32_bf16 v[126:129], v[146:149], v[168:171], v[126:129]
	v_mfma_f32_16x16x32_bf16 v[122:125], v[154:157], v[168:171], v[122:125]
	v_mfma_f32_16x16x32_bf16 v[110:113], v[146:149], v[186:189], v[110:113]
	v_mfma_f32_16x16x32_bf16 v[106:109], v[154:157], v[186:189], v[106:109]
	v_mfma_f32_16x16x32_bf16 v[94:97], v[146:149], v[194:197], v[94:97]
	v_mfma_f32_16x16x32_bf16 v[90:93], v[154:157], v[194:197], v[90:93]
	v_mfma_f32_16x16x32_bf16 v[78:81], v[146:149], v[202:205], v[78:81]
	v_mfma_f32_16x16x32_bf16 v[74:77], v[154:157], v[202:205], v[74:77]
	v_mfma_f32_16x16x32_bf16 v[126:129], v[150:153], v[172:175], v[126:129]
	v_mfma_f32_16x16x32_bf16 v[122:125], v[158:161], v[172:175], v[122:125]
	v_mfma_f32_16x16x32_bf16 v[110:113], v[150:153], v[190:193], v[110:113]
	v_mfma_f32_16x16x32_bf16 v[106:109], v[158:161], v[190:193], v[106:109]
	v_mfma_f32_16x16x32_bf16 v[94:97], v[150:153], v[198:201], v[94:97]
	v_mfma_f32_16x16x32_bf16 v[90:93], v[158:161], v[198:201], v[90:93]
	v_mfma_f32_16x16x32_bf16 v[78:81], v[150:153], v[206:209], v[78:81]
	v_mfma_f32_16x16x32_bf16 v[74:77], v[158:161], v[206:209], v[74:77]
	s_barrier
	s_add_i32 s51, 0, 0x14000
	v_add_u32_e32 v162, s51, v164
	s_add_i32 s48, s50, s29
	ds_read_b128 v[210:213], v162
	ds_read_b128 v[214:217], v162 offset:1024
	ds_read_b128 v[218:221], v162 offset:2048
	ds_read_b128 v[222:225], v162 offset:3072
	s_add_u32 s64, s16, 0x80
	s_addc_u32 s65, s17, 0
	s_mov_b32 m0, s48
	s_nop 0
	global_load_lds_dwordx4 v132, s[16:17]
	s_add_i32 m0, s48, 0x2000
	s_nop 0
	global_load_lds_dwordx4 v136, s[16:17]
	s_barrier
	s_waitcnt lgkmcnt(0)
	s_waitcnt lgkmcnt(0)
	v_mfma_f32_16x16x32_bf16 v[118:121], v[210:213], v[168:171], v[118:121]
	v_mfma_f32_16x16x32_bf16 v[114:117], v[218:221], v[168:171], v[114:117]
	v_mfma_f32_16x16x32_bf16 v[102:105], v[210:213], v[186:189], v[102:105]
	v_mfma_f32_16x16x32_bf16 v[98:101], v[218:221], v[186:189], v[98:101]
	v_mfma_f32_16x16x32_bf16 v[86:89], v[210:213], v[194:197], v[86:89]
	v_mfma_f32_16x16x32_bf16 v[82:85], v[218:221], v[194:197], v[82:85]
	v_mfma_f32_16x16x32_bf16 v[70:73], v[210:213], v[202:205], v[70:73]
	v_mfma_f32_16x16x32_bf16 v[66:69], v[218:221], v[202:205], v[66:69]
	v_mfma_f32_16x16x32_bf16 v[118:121], v[214:217], v[172:175], v[118:121]
	v_mfma_f32_16x16x32_bf16 v[114:117], v[222:225], v[172:175], v[114:117]
	v_mfma_f32_16x16x32_bf16 v[102:105], v[214:217], v[190:193], v[102:105]
	v_mfma_f32_16x16x32_bf16 v[98:101], v[222:225], v[190:193], v[98:101]
	v_mfma_f32_16x16x32_bf16 v[86:89], v[214:217], v[198:201], v[86:89]
	v_mfma_f32_16x16x32_bf16 v[82:85], v[222:225], v[198:201], v[82:85]
	v_mfma_f32_16x16x32_bf16 v[70:73], v[214:217], v[206:209], v[70:73]
	v_mfma_f32_16x16x32_bf16 v[66:69], v[222:225], v[206:209], v[66:69]
	s_barrier
	s_mov_b32 m0, s30
	s_add_u32 s62, s18, 0x80
	s_addc_u32 s63, s19, 0
	ds_read_b128 v[168:171], v166 offset:16384
	ds_read_b128 v[172:175], v166 offset:17408
	ds_read_b128 v[186:189], v166 offset:18432
	ds_read_b128 v[190:193], v166 offset:19456
	ds_read_b128 v[194:197], v166 offset:20480
	ds_read_b128 v[198:201], v166 offset:21504
	ds_read_b128 v[202:205], v166 offset:22528
	ds_read_b128 v[206:209], v166 offset:23552
	global_load_lds_dwordx4 v130, s[18:19]
	s_mov_b32 m0, s31
	s_nop 0
	global_load_lds_dwordx4 v134, s[18:19]
	s_waitcnt vmcnt(10)
	s_barrier
	s_waitcnt lgkmcnt(0)
	s_waitcnt lgkmcnt(0)
	v_mfma_f32_16x16x32_bf16 v[62:65], v[146:149], v[168:171], v[62:65]
	v_mfma_f32_16x16x32_bf16 v[58:61], v[154:157], v[168:171], v[58:61]
	v_mfma_f32_16x16x32_bf16 v[46:49], v[146:149], v[186:189], v[46:49]
	v_mfma_f32_16x16x32_bf16 v[42:45], v[154:157], v[186:189], v[42:45]
	v_mfma_f32_16x16x32_bf16 v[30:33], v[146:149], v[194:197], v[30:33]
	v_mfma_f32_16x16x32_bf16 v[26:29], v[154:157], v[194:197], v[26:29]
	v_mfma_f32_16x16x32_bf16 v[14:17], v[146:149], v[202:205], v[14:17]
	v_mfma_f32_16x16x32_bf16 v[10:13], v[154:157], v[202:205], v[10:13]
	v_mfma_f32_16x16x32_bf16 v[62:65], v[150:153], v[172:175], v[62:65]
	v_mfma_f32_16x16x32_bf16 v[58:61], v[158:161], v[172:175], v[58:61]
	v_mfma_f32_16x16x32_bf16 v[46:49], v[150:153], v[190:193], v[46:49]
	v_mfma_f32_16x16x32_bf16 v[42:45], v[158:161], v[190:193], v[42:45]
	v_mfma_f32_16x16x32_bf16 v[30:33], v[150:153], v[198:201], v[30:33]
	v_mfma_f32_16x16x32_bf16 v[26:29], v[158:161], v[198:201], v[26:29]
	v_mfma_f32_16x16x32_bf16 v[14:17], v[150:153], v[206:209], v[14:17]
	v_mfma_f32_16x16x32_bf16 v[10:13], v[158:161], v[206:209], v[10:13]
	s_barrier
	v_add_u32_e32 v158, 0x18000, v164
	ds_read_b128 v[146:149], v158
	ds_read_b128 v[150:153], v158 offset:1024
	ds_read_b128 v[154:157], v158 offset:2048
	ds_read_b128 v[158:161], v158 offset:3072
	s_add_u32 s48, s16, 0x80000
	s_addc_u32 s49, s17, 0
	s_add_i32 s50, s51, s29
	s_mov_b32 m0, s50
	s_nop 0
	global_load_lds_dwordx4 v132, s[48:49]
	s_add_i32 m0, s50, 0x2000
	s_nop 0
	global_load_lds_dwordx4 v136, s[48:49]
	s_waitcnt vmcnt(6)
	s_barrier
	v_mfma_f32_16x16x32_bf16 v[54:57], v[210:213], v[168:171], v[54:57]
	v_mfma_f32_16x16x32_bf16 v[50:53], v[218:221], v[168:171], v[50:53]
	v_mfma_f32_16x16x32_bf16 v[38:41], v[210:213], v[186:189], v[38:41]
	v_mfma_f32_16x16x32_bf16 v[34:37], v[218:221], v[186:189], v[34:37]
	v_mfma_f32_16x16x32_bf16 v[22:25], v[210:213], v[194:197], v[22:25]
	v_mfma_f32_16x16x32_bf16 v[18:21], v[218:221], v[194:197], v[18:21]
	v_mfma_f32_16x16x32_bf16 v[6:9], v[210:213], v[202:205], v[6:9]
	v_mfma_f32_16x16x32_bf16 v[2:5], v[218:221], v[202:205], v[2:5]
	v_mfma_f32_16x16x32_bf16 v[54:57], v[214:217], v[172:175], v[54:57]
	v_mfma_f32_16x16x32_bf16 v[50:53], v[222:225], v[172:175], v[50:53]
	v_mfma_f32_16x16x32_bf16 v[38:41], v[214:217], v[190:193], v[38:41]
	v_mfma_f32_16x16x32_bf16 v[34:37], v[222:225], v[190:193], v[34:37]
	v_mfma_f32_16x16x32_bf16 v[22:25], v[214:217], v[198:201], v[22:25]
	v_mfma_f32_16x16x32_bf16 v[18:21], v[222:225], v[198:201], v[18:21]
	v_mfma_f32_16x16x32_bf16 v[6:9], v[214:217], v[206:209], v[6:9]
	v_mfma_f32_16x16x32_bf16 v[2:5], v[222:225], v[206:209], v[2:5]
	s_barrier
	s_add_i32 s48, 0, 0x18000
	s_add_u32 s18, s18, s80
	s_addc_u32 s19, s19, 0
	s_mov_b32 m0, s34
	ds_read_b128 v[168:171], v166 offset:32768
	ds_read_b128 v[172:175], v166 offset:33792
	ds_read_b128 v[186:189], v166 offset:34816
	ds_read_b128 v[190:193], v166 offset:35840
	ds_read_b128 v[194:197], v166 offset:36864
	ds_read_b128 v[198:201], v166 offset:37888
	ds_read_b128 v[202:205], v166 offset:38912
	ds_read_b128 v[206:209], v166 offset:39936
	global_load_lds_dwordx4 v130, s[18:19]
	s_mov_b32 m0, s35
	s_nop 0
	global_load_lds_dwordx4 v134, s[18:19]
	s_waitcnt lgkmcnt(8)
	s_barrier
	s_waitcnt lgkmcnt(0)
	s_waitcnt lgkmcnt(0)
	v_mfma_f32_16x16x32_bf16 v[126:129], v[146:149], v[168:171], v[126:129]
	v_mfma_f32_16x16x32_bf16 v[122:125], v[154:157], v[168:171], v[122:125]
	v_mfma_f32_16x16x32_bf16 v[110:113], v[146:149], v[186:189], v[110:113]
	v_mfma_f32_16x16x32_bf16 v[106:109], v[154:157], v[186:189], v[106:109]
	v_mfma_f32_16x16x32_bf16 v[94:97], v[146:149], v[194:197], v[94:97]
	v_mfma_f32_16x16x32_bf16 v[90:93], v[154:157], v[194:197], v[90:93]
	v_mfma_f32_16x16x32_bf16 v[78:81], v[146:149], v[202:205], v[78:81]
	v_mfma_f32_16x16x32_bf16 v[74:77], v[154:157], v[202:205], v[74:77]
	v_mfma_f32_16x16x32_bf16 v[126:129], v[150:153], v[172:175], v[126:129]
	v_mfma_f32_16x16x32_bf16 v[122:125], v[158:161], v[172:175], v[122:125]
	v_mfma_f32_16x16x32_bf16 v[110:113], v[150:153], v[190:193], v[110:113]
	v_mfma_f32_16x16x32_bf16 v[106:109], v[158:161], v[190:193], v[106:109]
	v_mfma_f32_16x16x32_bf16 v[94:97], v[150:153], v[198:201], v[94:97]
	v_mfma_f32_16x16x32_bf16 v[90:93], v[158:161], v[198:201], v[90:93]
	v_mfma_f32_16x16x32_bf16 v[78:81], v[150:153], v[206:209], v[78:81]
	v_mfma_f32_16x16x32_bf16 v[74:77], v[158:161], v[206:209], v[74:77]
	s_barrier
	s_add_i32 s18, 0, 0x1c000
	s_add_i32 s19, s48, s29
	v_add_u32_e32 v167, s18, v164
	s_mov_b32 m0, s19
	ds_read_b128 v[210:213], v167
	ds_read_b128 v[214:217], v167 offset:1024
	ds_read_b128 v[218:221], v167 offset:2048
	ds_read_b128 v[222:225], v167 offset:3072
	global_load_lds_dwordx4 v132, s[64:65]
	s_add_i32 m0, s19, 0x2000
	s_nop 0
	global_load_lds_dwordx4 v136, s[64:65]
	s_barrier
	s_waitcnt lgkmcnt(0)
	s_waitcnt lgkmcnt(0)
	v_mfma_f32_16x16x32_bf16 v[118:121], v[210:213], v[168:171], v[118:121]
	v_mfma_f32_16x16x32_bf16 v[114:117], v[218:221], v[168:171], v[114:117]
	v_mfma_f32_16x16x32_bf16 v[102:105], v[210:213], v[186:189], v[102:105]
	v_mfma_f32_16x16x32_bf16 v[98:101], v[218:221], v[186:189], v[98:101]
	v_mfma_f32_16x16x32_bf16 v[86:89], v[210:213], v[194:197], v[86:89]
	v_mfma_f32_16x16x32_bf16 v[82:85], v[218:221], v[194:197], v[82:85]
	v_mfma_f32_16x16x32_bf16 v[70:73], v[210:213], v[202:205], v[70:73]
	v_mfma_f32_16x16x32_bf16 v[66:69], v[218:221], v[202:205], v[66:69]
	v_mfma_f32_16x16x32_bf16 v[118:121], v[214:217], v[172:175], v[118:121]
	v_mfma_f32_16x16x32_bf16 v[114:117], v[222:225], v[172:175], v[114:117]
	v_mfma_f32_16x16x32_bf16 v[102:105], v[214:217], v[190:193], v[102:105]
	v_mfma_f32_16x16x32_bf16 v[98:101], v[222:225], v[190:193], v[98:101]
	v_mfma_f32_16x16x32_bf16 v[86:89], v[214:217], v[198:201], v[86:89]
	v_mfma_f32_16x16x32_bf16 v[82:85], v[222:225], v[198:201], v[82:85]
	v_mfma_f32_16x16x32_bf16 v[70:73], v[214:217], v[206:209], v[70:73]
	v_mfma_f32_16x16x32_bf16 v[66:69], v[222:225], v[206:209], v[66:69]
	s_barrier
	s_mov_b32 m0, s38
	ds_read_b128 v[168:171], v166 offset:49152
	ds_read_b128 v[172:175], v166 offset:50176
	ds_read_b128 v[186:189], v166 offset:51200
	ds_read_b128 v[190:193], v166 offset:52224
	ds_read_b128 v[194:197], v166 offset:53248
	ds_read_b128 v[198:201], v166 offset:54272
	ds_read_b128 v[202:205], v166 offset:55296
	ds_read_b128 v[206:209], v166 offset:56320
	global_load_lds_dwordx4 v130, s[62:63]
	s_mov_b32 m0, s39
	s_nop 0
	global_load_lds_dwordx4 v134, s[62:63]
	s_waitcnt vmcnt(10)
	s_barrier
	s_waitcnt lgkmcnt(0)
	s_waitcnt lgkmcnt(0)
	v_mfma_f32_16x16x32_bf16 v[62:65], v[146:149], v[168:171], v[62:65]
	v_mfma_f32_16x16x32_bf16 v[58:61], v[154:157], v[168:171], v[58:61]
	v_mfma_f32_16x16x32_bf16 v[46:49], v[146:149], v[186:189], v[46:49]
	v_mfma_f32_16x16x32_bf16 v[42:45], v[154:157], v[186:189], v[42:45]
	v_mfma_f32_16x16x32_bf16 v[30:33], v[146:149], v[194:197], v[30:33]
	v_mfma_f32_16x16x32_bf16 v[26:29], v[154:157], v[194:197], v[26:29]
	v_mfma_f32_16x16x32_bf16 v[14:17], v[146:149], v[202:205], v[14:17]
	v_mfma_f32_16x16x32_bf16 v[10:13], v[154:157], v[202:205], v[10:13]
	v_mfma_f32_16x16x32_bf16 v[62:65], v[150:153], v[172:175], v[62:65]
	v_mfma_f32_16x16x32_bf16 v[58:61], v[158:161], v[172:175], v[58:61]
	v_mfma_f32_16x16x32_bf16 v[46:49], v[150:153], v[190:193], v[46:49]
	v_mfma_f32_16x16x32_bf16 v[42:45], v[158:161], v[190:193], v[42:45]
	v_mfma_f32_16x16x32_bf16 v[30:33], v[150:153], v[198:201], v[30:33]
	v_mfma_f32_16x16x32_bf16 v[26:29], v[158:161], v[198:201], v[26:29]
	v_mfma_f32_16x16x32_bf16 v[14:17], v[150:153], v[206:209], v[14:17]
	v_mfma_f32_16x16x32_bf16 v[10:13], v[158:161], v[206:209], v[10:13]
	s_barrier
	v_add_u32_e32 v158, 0x10000, v164
	ds_read_b128 v[146:149], v158
	ds_read_b128 v[150:153], v158 offset:1024
	ds_read_b128 v[154:157], v158 offset:2048
	ds_read_b128 v[158:161], v158 offset:3072
	s_add_u32 s16, s16, 0x80080
	s_addc_u32 s17, s17, 0
	s_add_i32 s18, s18, s29
	s_mov_b32 m0, s18
	s_nop 0
	global_load_lds_dwordx4 v132, s[16:17]
	s_add_i32 m0, s18, 0x2000
	s_nop 0
	global_load_lds_dwordx4 v136, s[16:17]
	s_waitcnt vmcnt(6)
	s_barrier
	v_mfma_f32_16x16x32_bf16 v[54:57], v[210:213], v[168:171], v[54:57]
	v_mfma_f32_16x16x32_bf16 v[50:53], v[218:221], v[168:171], v[50:53]
	v_mfma_f32_16x16x32_bf16 v[38:41], v[210:213], v[186:189], v[38:41]
	v_mfma_f32_16x16x32_bf16 v[34:37], v[218:221], v[186:189], v[34:37]
	v_mfma_f32_16x16x32_bf16 v[22:25], v[210:213], v[194:197], v[22:25]
	v_mfma_f32_16x16x32_bf16 v[18:21], v[218:221], v[194:197], v[18:21]
	v_mfma_f32_16x16x32_bf16 v[6:9], v[210:213], v[202:205], v[6:9]
	v_mfma_f32_16x16x32_bf16 v[2:5], v[218:221], v[202:205], v[2:5]
	v_mfma_f32_16x16x32_bf16 v[54:57], v[214:217], v[172:175], v[54:57]
	v_mfma_f32_16x16x32_bf16 v[50:53], v[222:225], v[172:175], v[50:53]
	v_mfma_f32_16x16x32_bf16 v[38:41], v[214:217], v[190:193], v[38:41]
	v_mfma_f32_16x16x32_bf16 v[34:37], v[222:225], v[190:193], v[34:37]
	v_mfma_f32_16x16x32_bf16 v[22:25], v[214:217], v[198:201], v[22:25]
	v_mfma_f32_16x16x32_bf16 v[18:21], v[222:225], v[198:201], v[18:21]
	v_mfma_f32_16x16x32_bf16 v[6:9], v[214:217], v[206:209], v[6:9]
	v_mfma_f32_16x16x32_bf16 v[2:5], v[222:225], v[206:209], v[2:5]
	s_barrier
	s_add_i32 s47, s47, 2
	s_add_u32 s6, s6, 0x100
	s_addc_u32 s7, s7, 0
	s_cmp_gt_u32 s47, 29
	s_cbranch_scc0 .LBB0_1408
	s_waitcnt lgkmcnt(0)
	s_ashr_i32 s3, s33, 5
	s_mul_hi_i32 s7, s3, 0x9000
	s_mul_i32 s3, s3, 0x9000
	v_lshl_or_b32 v168, s43, 8, v165
	s_add_u32 s6, s36, s3
	s_addc_u32 s7, s37, s7
	v_ashrrev_i32_e32 v169, 31, v168
	v_lshl_add_u64 v[162:163], v[168:169], 2, s[6:7]
	global_load_dwordx4 v[142:145], v[162:163], off offset:16
	global_load_dwordx4 v[146:149], v[162:163], off
	v_mov_b32_e32 v158, v162
	v_mov_b32_e32 v159, v163
	v_lshl_add_u32 v162, s33, 8, v1
	v_ashrrev_i32_e32 v163, 31, v162
	v_lshlrev_b64 v[152:153], 12, v[162:163]
	v_lshl_add_u64 v[152:153], s[8:9], 0, v[152:153]
	v_lshl_add_u64 v[152:153], v[168:169], 1, v[152:153]
	v_mov_b32_e32 v156, 0x10000
	v_mov_b32_e32 v157, 0
	global_load_dwordx4 v[174:177], v[152:153], off offset:2048
	global_load_dwordx4 v[186:189], v[152:153], off offset:2304
	v_lshl_add_u64 v[152:153], v[152:153], 0, v[156:157]
	global_load_dwordx4 v[190:193], v[152:153], off offset:2048
	global_load_dwordx4 v[194:197], v[152:153], off offset:2304
	v_lshl_add_u64 v[152:153], v[152:153], 0, v[156:157]
	global_load_dwordx4 v[198:201], v[152:153], off offset:2048
	global_load_dwordx4 v[202:205], v[152:153], off offset:2304
	v_lshl_add_u64 v[152:153], v[152:153], 0, v[156:157]
	global_load_dwordx4 v[206:209], v[152:153], off offset:2048
	global_load_dwordx4 v[210:213], v[152:153], off offset:2304
	v_mov_b32_e32 v156, 0x50000
	v_lshl_add_u64 v[152:153], v[152:153], 0, v[156:157]
	v_mov_b32_e32 v156, 0x10000
	global_load_dwordx4 v[214:217], v[152:153], off offset:2048
	global_load_dwordx4 v[218:221], v[152:153], off offset:2304
	v_lshl_add_u64 v[152:153], v[152:153], 0, v[156:157]
	global_load_dwordx4 v[222:225], v[152:153], off offset:2048
	global_load_dwordx4 v[226:229], v[152:153], off offset:2304
	v_lshl_add_u64 v[152:153], v[152:153], 0, v[156:157]
	global_load_dwordx4 v[230:233], v[152:153], off offset:2048
	global_load_dwordx4 v[236:239], v[152:153], off offset:2304
	v_lshl_add_u64 v[152:153], v[152:153], 0, v[156:157]
	global_load_dwordx4 v[246:249], v[152:153], off offset:2048
	global_load_dwordx4 v[250:253], v[152:153], off offset:2304
	s_mov_b64 s[6:7], 0x80000
	s_and_b64 vcc, exec, s[4:5]
	s_mov_b32 s43, s2
	s_mov_b64 s[16:17], s[12:13]
	s_mov_b64 s[14:15], s[10:11]
	s_waitcnt vmcnt(16)
	v_pk_add_f32 v[150:151], v[144:145], 1.0 op_sel_hi:[1,0]
	v_pk_add_f32 v[154:155], v[142:143], 1.0 op_sel_hi:[1,0]
	global_load_dwordx4 v[142:145], v[158:159], off offset:512
	global_load_dwordx4 v[158:161], v[158:159], off offset:528
	v_pk_add_f32 v[156:157], v[146:147], 1.0 op_sel_hi:[1,0]
	v_pk_add_f32 v[152:153], v[148:149], 1.0 op_sel_hi:[1,0]
	s_mov_b32 s33, s42
	s_waitcnt vmcnt(0)
	v_pk_add_f32 v[146:147], v[144:145], 1.0 op_sel_hi:[1,0]
	v_pk_add_f32 v[144:145], v[158:159], 1.0 op_sel_hi:[1,0]
	v_lshlrev_b64 v[158:159], 12, v[162:163]
	v_pk_add_f32 v[148:149], v[142:143], 1.0 op_sel_hi:[1,0]
	v_pk_add_f32 v[142:143], v[160:161], 1.0 op_sel_hi:[1,0]
	v_lshl_add_u64 v[158:159], s[8:9], 0, v[158:159]
	v_lshlrev_b64 v[160:161], 1, v[168:169]
	v_lshl_add_u64 v[158:159], v[158:159], 0, v[160:161]
	v_mov_b32_e32 v168, v174
	v_mov_b32_e32 v169, v175
	v_mov_b32_e32 v170, v176
	v_mov_b32_e32 v171, v177
	s_nop 0
	v_lshlrev_b32_e32 v172, 16, v168
	v_and_b32_e32 v173, 0xffff0000, v168
	v_lshlrev_b32_e32 v168, 16, v169
	v_and_b32_e32 v169, 0xffff0000, v169
	v_pk_fma_f32 v[128:129], v[128:129], v[152:153], v[168:169]
	v_lshlrev_b32_e32 v168, 16, v170
	v_and_b32_e32 v169, 0xffff0000, v170
	v_pk_fma_f32 v[168:169], v[122:123], v[154:155], v[168:169]
	v_lshlrev_b32_e32 v122, 16, v171
	v_and_b32_e32 v123, 0xffff0000, v171
	v_pk_fma_f32 v[126:127], v[126:127], v[156:157], v[172:173]
	v_pk_fma_f32 v[170:171], v[124:125], v[150:151], v[122:123]
	v_cvt_pk_bf16_f32 v122, v126, v127
	v_cvt_pk_bf16_f32 v123, v128, v129
	v_cvt_pk_bf16_f32 v124, v168, v169
	v_cvt_pk_bf16_f32 v125, v170, v171
	global_store_dwordx4 v[158:159], v[122:125], off offset:2048
	s_nop 1
	v_mov_b32_e32 v122, v186
	v_mov_b32_e32 v123, v187
	v_mov_b32_e32 v124, v188
	v_mov_b32_e32 v125, v189
	s_nop 0
	v_lshlrev_b32_e32 v126, 16, v122
	v_and_b32_e32 v127, 0xffff0000, v122
	v_lshlrev_b32_e32 v122, 16, v123
	v_and_b32_e32 v123, 0xffff0000, v123
	v_pk_fma_f32 v[120:121], v[120:121], v[146:147], v[122:123]
	v_lshlrev_b32_e32 v122, 16, v124
	v_and_b32_e32 v123, 0xffff0000, v124
	v_pk_fma_f32 v[122:123], v[114:115], v[144:145], v[122:123]
	v_lshlrev_b32_e32 v114, 16, v125
	v_and_b32_e32 v115, 0xffff0000, v125
	v_pk_fma_f32 v[118:119], v[118:119], v[148:149], v[126:127]
	v_pk_fma_f32 v[124:125], v[116:117], v[142:143], v[114:115]
	v_cvt_pk_bf16_f32 v114, v118, v119
	v_cvt_pk_bf16_f32 v115, v120, v121
	v_cvt_pk_bf16_f32 v116, v122, v123
	v_cvt_pk_bf16_f32 v117, v124, v125
	global_store_dwordx4 v[158:159], v[114:117], off offset:2304
	s_nop 1
	v_or_b32_e32 v114, 16, v162
	v_ashrrev_i32_e32 v115, 31, v114
	v_lshlrev_b64 v[114:115], 12, v[114:115]
	v_lshl_add_u64 v[114:115], s[8:9], 0, v[114:115]
	v_lshl_add_u64 v[118:119], v[114:115], 0, v[160:161]
	v_mov_b32_e32 v114, v190
	v_mov_b32_e32 v115, v191
	v_mov_b32_e32 v116, v192
	v_mov_b32_e32 v117, v193
	s_nop 0
	v_lshlrev_b32_e32 v120, 16, v114
	v_and_b32_e32 v121, 0xffff0000, v114
	v_lshlrev_b32_e32 v114, 16, v115
	v_and_b32_e32 v115, 0xffff0000, v115
	v_pk_fma_f32 v[112:113], v[112:113], v[152:153], v[114:115]
	v_lshlrev_b32_e32 v114, 16, v116
	v_and_b32_e32 v115, 0xffff0000, v116
	v_pk_fma_f32 v[114:115], v[106:107], v[154:155], v[114:115]
	v_lshlrev_b32_e32 v106, 16, v117
	v_and_b32_e32 v107, 0xffff0000, v117
	v_pk_fma_f32 v[110:111], v[110:111], v[156:157], v[120:121]
	v_pk_fma_f32 v[116:117], v[108:109], v[150:151], v[106:107]
	v_cvt_pk_bf16_f32 v106, v110, v111
	v_cvt_pk_bf16_f32 v107, v112, v113
	v_cvt_pk_bf16_f32 v108, v114, v115
	v_cvt_pk_bf16_f32 v109, v116, v117
	global_store_dwordx4 v[118:119], v[106:109], off offset:2048
	s_nop 1
	v_mov_b32_e32 v106, v194
	v_mov_b32_e32 v107, v195
	v_mov_b32_e32 v108, v196
	v_mov_b32_e32 v109, v197
	s_nop 0
	v_lshlrev_b32_e32 v110, 16, v106
	v_and_b32_e32 v111, 0xffff0000, v106
	v_lshlrev_b32_e32 v106, 16, v107
	v_and_b32_e32 v107, 0xffff0000, v107
	v_pk_fma_f32 v[104:105], v[104:105], v[146:147], v[106:107]
	v_lshlrev_b32_e32 v106, 16, v108
	v_and_b32_e32 v107, 0xffff0000, v108
	v_pk_fma_f32 v[106:107], v[98:99], v[144:145], v[106:107]
	v_lshlrev_b32_e32 v98, 16, v109
	v_and_b32_e32 v99, 0xffff0000, v109
	v_pk_fma_f32 v[102:103], v[102:103], v[148:149], v[110:111]
	v_pk_fma_f32 v[108:109], v[100:101], v[142:143], v[98:99]
	v_cvt_pk_bf16_f32 v98, v102, v103
	v_cvt_pk_bf16_f32 v99, v104, v105
	v_cvt_pk_bf16_f32 v100, v106, v107
	v_cvt_pk_bf16_f32 v101, v108, v109
	global_store_dwordx4 v[118:119], v[98:101], off offset:2304
	s_nop 1
	v_or_b32_e32 v98, 32, v162
	v_ashrrev_i32_e32 v99, 31, v98
	v_lshlrev_b64 v[98:99], 12, v[98:99]
	v_lshl_add_u64 v[98:99], s[8:9], 0, v[98:99]
	v_lshl_add_u64 v[102:103], v[98:99], 0, v[160:161]
	v_mov_b32_e32 v98, v198
	v_mov_b32_e32 v99, v199
	v_mov_b32_e32 v100, v200
	v_mov_b32_e32 v101, v201
	s_nop 0
	v_lshlrev_b32_e32 v104, 16, v98
	v_and_b32_e32 v105, 0xffff0000, v98
	v_lshlrev_b32_e32 v98, 16, v99
	v_and_b32_e32 v99, 0xffff0000, v99
	v_pk_fma_f32 v[96:97], v[96:97], v[152:153], v[98:99]
	v_lshlrev_b32_e32 v98, 16, v100
	v_and_b32_e32 v99, 0xffff0000, v100
	v_pk_fma_f32 v[98:99], v[90:91], v[154:155], v[98:99]
	v_lshlrev_b32_e32 v90, 16, v101
	v_and_b32_e32 v91, 0xffff0000, v101
	v_pk_fma_f32 v[94:95], v[94:95], v[156:157], v[104:105]
	v_pk_fma_f32 v[100:101], v[92:93], v[150:151], v[90:91]
	v_cvt_pk_bf16_f32 v90, v94, v95
	v_cvt_pk_bf16_f32 v91, v96, v97
	v_cvt_pk_bf16_f32 v92, v98, v99
	v_cvt_pk_bf16_f32 v93, v100, v101
	global_store_dwordx4 v[102:103], v[90:93], off offset:2048
	s_nop 1
	v_mov_b32_e32 v90, v202
	v_mov_b32_e32 v91, v203
	v_mov_b32_e32 v92, v204
	v_mov_b32_e32 v93, v205
	s_nop 0
	v_lshlrev_b32_e32 v94, 16, v90
	v_and_b32_e32 v95, 0xffff0000, v90
	v_lshlrev_b32_e32 v90, 16, v91
	v_and_b32_e32 v91, 0xffff0000, v91
	v_pk_fma_f32 v[88:89], v[88:89], v[146:147], v[90:91]
	v_lshlrev_b32_e32 v90, 16, v92
	v_and_b32_e32 v91, 0xffff0000, v92
	v_pk_fma_f32 v[90:91], v[82:83], v[144:145], v[90:91]
	v_lshlrev_b32_e32 v82, 16, v93
	v_and_b32_e32 v83, 0xffff0000, v93
	v_pk_fma_f32 v[86:87], v[86:87], v[148:149], v[94:95]
	v_pk_fma_f32 v[92:93], v[84:85], v[142:143], v[82:83]
	v_cvt_pk_bf16_f32 v82, v86, v87
	v_cvt_pk_bf16_f32 v83, v88, v89
	v_cvt_pk_bf16_f32 v84, v90, v91
	v_cvt_pk_bf16_f32 v85, v92, v93
	global_store_dwordx4 v[102:103], v[82:85], off offset:2304
	s_nop 1
	v_or_b32_e32 v82, 48, v162
	v_ashrrev_i32_e32 v83, 31, v82
	v_lshlrev_b64 v[82:83], 12, v[82:83]
	v_lshl_add_u64 v[82:83], s[8:9], 0, v[82:83]
	v_lshl_add_u64 v[82:83], v[82:83], 0, v[160:161]
	v_mov_b32_e32 v84, v206
	v_mov_b32_e32 v85, v207
	v_mov_b32_e32 v86, v208
	v_mov_b32_e32 v87, v209
	s_nop 0
	v_lshlrev_b32_e32 v88, 16, v84
	v_and_b32_e32 v89, 0xffff0000, v84
	v_lshlrev_b32_e32 v84, 16, v85
	v_and_b32_e32 v85, 0xffff0000, v85
	v_pk_fma_f32 v[80:81], v[80:81], v[152:153], v[84:85]
	v_lshlrev_b32_e32 v84, 16, v86
	v_and_b32_e32 v85, 0xffff0000, v86
	v_pk_fma_f32 v[84:85], v[74:75], v[154:155], v[84:85]
	v_lshlrev_b32_e32 v74, 16, v87
	v_and_b32_e32 v75, 0xffff0000, v87
	v_pk_fma_f32 v[78:79], v[78:79], v[156:157], v[88:89]
	v_pk_fma_f32 v[86:87], v[76:77], v[150:151], v[74:75]
	v_cvt_pk_bf16_f32 v74, v78, v79
	v_cvt_pk_bf16_f32 v75, v80, v81
	v_cvt_pk_bf16_f32 v76, v84, v85
	v_cvt_pk_bf16_f32 v77, v86, v87
	global_store_dwordx4 v[82:83], v[74:77], off offset:2048
	s_nop 1
	v_mov_b32_e32 v74, v210
	v_mov_b32_e32 v75, v211
	v_mov_b32_e32 v76, v212
	v_mov_b32_e32 v77, v213
	s_nop 0
	v_lshlrev_b32_e32 v78, 16, v74
	v_and_b32_e32 v79, 0xffff0000, v74
	v_lshlrev_b32_e32 v74, 16, v75
	v_and_b32_e32 v75, 0xffff0000, v75
	v_pk_fma_f32 v[72:73], v[72:73], v[146:147], v[74:75]
	v_lshlrev_b32_e32 v74, 16, v76
	v_and_b32_e32 v75, 0xffff0000, v76
	v_pk_fma_f32 v[74:75], v[66:67], v[144:145], v[74:75]
	v_lshlrev_b32_e32 v66, 16, v77
	v_and_b32_e32 v67, 0xffff0000, v77
	v_pk_fma_f32 v[70:71], v[70:71], v[148:149], v[78:79]
	v_pk_fma_f32 v[76:77], v[68:69], v[142:143], v[66:67]
	v_cvt_pk_bf16_f32 v66, v70, v71
	v_cvt_pk_bf16_f32 v67, v72, v73
	v_cvt_pk_bf16_f32 v68, v74, v75
	v_cvt_pk_bf16_f32 v69, v76, v77
	v_lshl_add_u64 v[70:71], v[158:159], 0, s[6:7]
	global_store_dwordx4 v[82:83], v[66:69], off offset:2304
	s_nop 1
	v_mov_b32_e32 v66, v214
	v_mov_b32_e32 v67, v215
	v_mov_b32_e32 v68, v216
	v_mov_b32_e32 v69, v217
	s_mov_b64 s[6:7], 0x90000
	s_nop 0
	v_lshlrev_b32_e32 v72, 16, v66
	v_and_b32_e32 v73, 0xffff0000, v66
	v_lshlrev_b32_e32 v66, 16, v67
	v_and_b32_e32 v67, 0xffff0000, v67
	v_pk_fma_f32 v[64:65], v[64:65], v[152:153], v[66:67]
	v_lshlrev_b32_e32 v66, 16, v68
	v_and_b32_e32 v67, 0xffff0000, v68
	v_pk_fma_f32 v[66:67], v[58:59], v[154:155], v[66:67]
	v_lshlrev_b32_e32 v58, 16, v69
	v_and_b32_e32 v59, 0xffff0000, v69
	v_pk_fma_f32 v[62:63], v[62:63], v[156:157], v[72:73]
	v_pk_fma_f32 v[68:69], v[60:61], v[150:151], v[58:59]
	v_cvt_pk_bf16_f32 v58, v62, v63
	v_cvt_pk_bf16_f32 v59, v64, v65
	v_cvt_pk_bf16_f32 v60, v66, v67
	v_cvt_pk_bf16_f32 v61, v68, v69
	global_store_dwordx4 v[70:71], v[58:61], off offset:2048
	s_nop 1
	v_mov_b32_e32 v58, v218
	v_mov_b32_e32 v59, v219
	v_mov_b32_e32 v60, v220
	v_mov_b32_e32 v61, v221
	s_nop 0
	v_lshlrev_b32_e32 v62, 16, v58
	v_and_b32_e32 v63, 0xffff0000, v58
	v_lshlrev_b32_e32 v58, 16, v59
	v_and_b32_e32 v59, 0xffff0000, v59
	v_pk_fma_f32 v[56:57], v[56:57], v[146:147], v[58:59]
	v_lshlrev_b32_e32 v58, 16, v60
	v_and_b32_e32 v59, 0xffff0000, v60
	v_pk_fma_f32 v[58:59], v[50:51], v[144:145], v[58:59]
	v_lshlrev_b32_e32 v50, 16, v61
	v_and_b32_e32 v51, 0xffff0000, v61
	v_pk_fma_f32 v[54:55], v[54:55], v[148:149], v[62:63]
	v_pk_fma_f32 v[60:61], v[52:53], v[142:143], v[50:51]
	v_cvt_pk_bf16_f32 v50, v54, v55
	v_cvt_pk_bf16_f32 v51, v56, v57
	v_cvt_pk_bf16_f32 v52, v58, v59
	v_cvt_pk_bf16_f32 v53, v60, v61
	v_lshl_add_u64 v[54:55], v[158:159], 0, s[6:7]
	global_store_dwordx4 v[70:71], v[50:53], off offset:2304
	s_nop 1
	v_mov_b32_e32 v50, v222
	v_mov_b32_e32 v51, v223
	v_mov_b32_e32 v52, v224
	v_mov_b32_e32 v53, v225
	s_mov_b64 s[6:7], 0xa0000
	s_nop 0
	v_lshlrev_b32_e32 v56, 16, v50
	v_and_b32_e32 v57, 0xffff0000, v50
	v_lshlrev_b32_e32 v50, 16, v51
	v_and_b32_e32 v51, 0xffff0000, v51
	v_pk_fma_f32 v[48:49], v[48:49], v[152:153], v[50:51]
	v_lshlrev_b32_e32 v50, 16, v52
	v_and_b32_e32 v51, 0xffff0000, v52
	v_pk_fma_f32 v[50:51], v[42:43], v[154:155], v[50:51]
	v_lshlrev_b32_e32 v42, 16, v53
	v_and_b32_e32 v43, 0xffff0000, v53
	v_pk_fma_f32 v[46:47], v[46:47], v[156:157], v[56:57]
	v_pk_fma_f32 v[52:53], v[44:45], v[150:151], v[42:43]
	v_cvt_pk_bf16_f32 v42, v46, v47
	v_cvt_pk_bf16_f32 v43, v48, v49
	v_cvt_pk_bf16_f32 v44, v50, v51
	v_cvt_pk_bf16_f32 v45, v52, v53
	global_store_dwordx4 v[54:55], v[42:45], off offset:2048
	s_nop 1
	v_mov_b32_e32 v42, v226
	v_mov_b32_e32 v43, v227
	v_mov_b32_e32 v44, v228
	v_mov_b32_e32 v45, v229
	s_nop 0
	v_lshlrev_b32_e32 v46, 16, v42
	v_and_b32_e32 v47, 0xffff0000, v42
	v_lshlrev_b32_e32 v42, 16, v43
	v_and_b32_e32 v43, 0xffff0000, v43
	v_pk_fma_f32 v[40:41], v[40:41], v[146:147], v[42:43]
	v_lshlrev_b32_e32 v42, 16, v44
	v_and_b32_e32 v43, 0xffff0000, v44
	v_pk_fma_f32 v[42:43], v[34:35], v[144:145], v[42:43]
	v_lshlrev_b32_e32 v34, 16, v45
	v_and_b32_e32 v35, 0xffff0000, v45
	v_pk_fma_f32 v[38:39], v[38:39], v[148:149], v[46:47]
	v_pk_fma_f32 v[44:45], v[36:37], v[142:143], v[34:35]
	v_cvt_pk_bf16_f32 v34, v38, v39
	v_cvt_pk_bf16_f32 v35, v40, v41
	v_cvt_pk_bf16_f32 v36, v42, v43
	v_cvt_pk_bf16_f32 v37, v44, v45
	v_lshl_add_u64 v[38:39], v[158:159], 0, s[6:7]
	global_store_dwordx4 v[54:55], v[34:37], off offset:2304
	s_nop 1
	v_mov_b32_e32 v34, v230
	v_mov_b32_e32 v35, v231
	v_mov_b32_e32 v36, v232
	v_mov_b32_e32 v37, v233
	s_mov_b64 s[6:7], 0xb0000
	s_nop 0
	v_lshlrev_b32_e32 v40, 16, v34
	v_and_b32_e32 v41, 0xffff0000, v34
	v_lshlrev_b32_e32 v34, 16, v35
	v_and_b32_e32 v35, 0xffff0000, v35
	v_pk_fma_f32 v[32:33], v[32:33], v[152:153], v[34:35]
	v_lshlrev_b32_e32 v34, 16, v36
	v_and_b32_e32 v35, 0xffff0000, v36
	v_pk_fma_f32 v[34:35], v[26:27], v[154:155], v[34:35]
	v_lshlrev_b32_e32 v26, 16, v37
	v_and_b32_e32 v27, 0xffff0000, v37
	v_pk_fma_f32 v[30:31], v[30:31], v[156:157], v[40:41]
	v_pk_fma_f32 v[36:37], v[28:29], v[150:151], v[26:27]
	v_cvt_pk_bf16_f32 v26, v30, v31
	v_cvt_pk_bf16_f32 v27, v32, v33
	v_cvt_pk_bf16_f32 v28, v34, v35
	v_cvt_pk_bf16_f32 v29, v36, v37
	global_store_dwordx4 v[38:39], v[26:29], off offset:2048
	s_nop 1
	v_mov_b32_e32 v26, v236
	v_mov_b32_e32 v27, v237
	v_mov_b32_e32 v28, v238
	v_mov_b32_e32 v29, v239
	s_nop 0
	v_lshlrev_b32_e32 v30, 16, v26
	v_and_b32_e32 v31, 0xffff0000, v26
	v_lshlrev_b32_e32 v26, 16, v27
	v_and_b32_e32 v27, 0xffff0000, v27
	v_pk_fma_f32 v[24:25], v[24:25], v[146:147], v[26:27]
	v_lshlrev_b32_e32 v26, 16, v28
	v_and_b32_e32 v27, 0xffff0000, v28
	v_pk_fma_f32 v[26:27], v[18:19], v[144:145], v[26:27]
	v_lshlrev_b32_e32 v18, 16, v29
	v_and_b32_e32 v19, 0xffff0000, v29
	v_pk_fma_f32 v[22:23], v[22:23], v[148:149], v[30:31]
	v_pk_fma_f32 v[28:29], v[20:21], v[142:143], v[18:19]
	v_cvt_pk_bf16_f32 v18, v22, v23
	v_cvt_pk_bf16_f32 v19, v24, v25
	v_cvt_pk_bf16_f32 v20, v26, v27
	v_cvt_pk_bf16_f32 v21, v28, v29
	global_store_dwordx4 v[38:39], v[18:21], off offset:2304
	s_nop 1
	v_lshl_add_u64 v[18:19], v[158:159], 0, s[6:7]
	v_mov_b32_e32 v20, v246
	v_mov_b32_e32 v21, v247
	v_mov_b32_e32 v22, v248
	v_mov_b32_e32 v23, v249
	s_nop 0
	v_lshlrev_b32_e32 v24, 16, v20
	v_and_b32_e32 v25, 0xffff0000, v20
	v_lshlrev_b32_e32 v20, 16, v21
	v_and_b32_e32 v21, 0xffff0000, v21
	v_pk_fma_f32 v[16:17], v[16:17], v[152:153], v[20:21]
	v_lshlrev_b32_e32 v20, 16, v22
	v_and_b32_e32 v21, 0xffff0000, v22
	v_pk_fma_f32 v[20:21], v[10:11], v[154:155], v[20:21]
	v_lshlrev_b32_e32 v10, 16, v23
	v_and_b32_e32 v11, 0xffff0000, v23
	v_pk_fma_f32 v[14:15], v[14:15], v[156:157], v[24:25]
	v_pk_fma_f32 v[22:23], v[12:13], v[150:151], v[10:11]
	v_cvt_pk_bf16_f32 v10, v14, v15
	v_cvt_pk_bf16_f32 v11, v16, v17
	v_cvt_pk_bf16_f32 v12, v20, v21
	v_cvt_pk_bf16_f32 v13, v22, v23
	global_store_dwordx4 v[18:19], v[10:13], off offset:2048
	s_nop 1
	v_mov_b32_e32 v10, v250
	v_mov_b32_e32 v11, v251
	v_mov_b32_e32 v12, v252
	v_mov_b32_e32 v13, v253
	s_nop 0
	v_lshlrev_b32_e32 v14, 16, v10
	v_and_b32_e32 v15, 0xffff0000, v10
	v_lshlrev_b32_e32 v10, 16, v11
	v_and_b32_e32 v11, 0xffff0000, v11
	v_pk_fma_f32 v[8:9], v[8:9], v[146:147], v[10:11]
	v_lshlrev_b32_e32 v10, 16, v12
	v_and_b32_e32 v11, 0xffff0000, v12
	v_pk_fma_f32 v[10:11], v[2:3], v[144:145], v[10:11]
	v_lshlrev_b32_e32 v2, 16, v13
	v_and_b32_e32 v3, 0xffff0000, v13
	v_pk_fma_f32 v[6:7], v[6:7], v[148:149], v[14:15]
	v_pk_fma_f32 v[12:13], v[4:5], v[142:143], v[2:3]
	v_cvt_pk_bf16_f32 v2, v6, v7
	v_cvt_pk_bf16_f32 v3, v8, v9
	v_cvt_pk_bf16_f32 v4, v10, v11
	v_cvt_pk_bf16_f32 v5, v12, v13
	global_store_dwordx4 v[18:19], v[2:5], off offset:2304
	s_cbranch_vccz .LBB0_1399
	s_waitcnt vmcnt(0)
	s_cmpk_gt_u32 s22, 0xff
	s_cbranch_scc1 .LBB0_1412
	s_barrier
